# GEMM loops: s_setprio hoisted above the phase barrier and the duplicate lgkmcnt wait after it removed; scanner computes next chunk LDS addresses before its barrier
# speedup vs baseline: 1.0133x; 1.0133x over previous
; #define PG8_STAGE(bufoff, gbase, voff) do { _Pragma("unroll") for (int _i = 0; _i < 2; ++_i) \
;         __builtin_amdgcn_global_load_lds((const unsigned*)((const char*)(gbase) + (voff)[_i]), (PG8_LAS unsigned*)(lds + (bufoff) + ldsw + _i * 8192), 16, 0, 0); } while (0)
; #define PG8_LDA(dst, b, h) do { _Pragma("unroll") for (int m = 0; m < 4; ++m) _Pragma("unroll") for (int k = 0; k < 2; ++k) dst[m][k] = *(const PG8_LAS bf16x8*)(lds + PG8_SA(b, h) + aoff + m * 2048 + k * 1024); } while (0)
; #define PG8_LDB(dst, b, h) do { _Pragma("unroll") for (int n = 0; n < 2; ++n) _Pragma("unroll") for (int k = 0; k < 2; ++k) dst[n][k] = *(const PG8_LAS bf16x8*)(lds + PG8_SB(b, h) + boff + n * 2048 + k * 1024); } while (0)
; #define PG8_MMA(ai, bj, At, Bt) do { __builtin_amdgcn_s_setprio(1); _Pragma("unroll") for (int m = 0; m < 4; ++m) _Pragma("unroll") for (int n = 0; n < 2; ++n) _Pragma("unroll") for (int k = 0; k < 2; ++k) \
;         acc[ai][bj][m][n] = __builtin_amdgcn_mfma_f32_16x16x32_bf16(Bt[n][k], At[m][k], acc[ai][bj][m][n], 0, 0, 0); __builtin_amdgcn_s_setprio(0); } while (0)
; #define PG8_WAIT_V(n) asm volatile("s_waitcnt vmcnt(" #n ")" ::: "memory")
; #define PG8_WAIT_L(n) asm volatile("s_waitcnt lgkmcnt(" #n ")" ::: "memory")
; #define PG8_BAR __builtin_amdgcn_s_barrier()
; #define PG8_SCHED __builtin_amdgcn_sched_barrier(0)
; template <class Epi, class Sched, bool ALIGN_EPI = false, bool SP2 = false>
; __device__ __forceinline__ void gemm_phase(PG8_LAS unsigned char* lds, const Gemm g, const Sched& S, const Epi& E) {
;     ...
;             PG8_LDB(B0, 0, 0); PG8_LDB(B1, 0, 1); PG8_SCHED; PG8_LDA(At, 0, 0); PG8_STAGE(PG8_SA(1, 1), a1 + hstep, voffA);
;             PG8_WAIT_V(8); PG8_WAIT_L(0); PG8_BAR; PG8_MMA(0, 0, At, B0); PG8_MMA(0, 1, At, B1); PG8_BAR; PG8_SCHED;
;             PG8_LDA(At, 0, 1); PG8_STAGE(PG8_SB(0, 0), b2, voffB); PG8_STAGE(PG8_SB(0, 1), b2 + hstep, voffB); PG8_STAGE(PG8_SA(0, 0), a2, voffA);
;             PG8_WAIT_V(8); PG8_WAIT_L(0); PG8_BAR; PG8_MMA(1, 0, At, B0); PG8_MMA(1, 1, At, B1); PG8_BAR; PG8_SCHED;
;             PG8_LDB(B0, 1, 0); PG8_LDB(B1, 1, 1); PG8_SCHED; PG8_LDA(At, 1, 0); PG8_STAGE(PG8_SA(0, 1), a2 + hstep, voffA);
.LBB0_38:
	s_add_u32 s62, s60, 0xfff80080
	s_addc_u32 s63, s61, -1
	s_add_i32 s86, 0, 0x10000
	s_cmp_eq_u32 s83, 28
	s_cselect_b32 s65, s2, s63
	s_cselect_b32 s64, s3, s62
	v_add_u32_e32 v142, s86, v156
	s_cselect_b32 s63, s53, s82
	s_cselect_b32 s62, s55, s79
	s_add_i32 s88, 0, 0x14000
	ds_read_b128 v[152:155], v142
	ds_read_b128 v[160:163], v142 offset:1024
	ds_read_b128 v[164:167], v142 offset:2048
	ds_read_b128 v[182:185], v142 offset:3072
	v_add_u32_e32 v142, s88, v156
	ds_read_b128 v[186:189], v142
	ds_read_b128 v[190:193], v142 offset:1024
	ds_read_b128 v[194:197], v142 offset:2048
	ds_read_b128 v[198:201], v142 offset:3072
	v_lshl_add_u64 v[142:143], s[60:61], 0, v[150:151]
	s_add_i32 m0, s69, 0xc000
	ds_read_b128 v[202:205], v158
	ds_read_b128 v[206:209], v158 offset:1024
	ds_read_b128 v[214:217], v158 offset:2048
	ds_read_b128 v[218:221], v158 offset:3072
	ds_read_b128 v[222:225], v158 offset:4096
	ds_read_b128 v[226:229], v158 offset:5120
	ds_read_b128 v[230:233], v158 offset:6144
	ds_read_b128 v[234:237], v158 offset:7168
	global_load_lds_dwordx4 v[142:143], off
	v_lshl_add_u64 v[142:143], s[60:61], 0, v[136:137]
	s_add_i32 m0, s69, 0xe000
	s_nop 0
	global_load_lds_dwordx4 v[142:143], off
	s_waitcnt vmcnt(8)
	s_waitcnt lgkmcnt(0)
	s_setprio 1
	s_barrier
	v_mfma_f32_16x16x32_bf16 v[126:129], v[152:155], v[202:205], v[126:129]
	v_mfma_f32_16x16x32_bf16 v[122:125], v[164:167], v[202:205], v[122:125]
	v_mfma_f32_16x16x32_bf16 v[110:113], v[152:155], v[214:217], v[110:113]
	v_mfma_f32_16x16x32_bf16 v[106:109], v[164:167], v[214:217], v[106:109]
	v_mfma_f32_16x16x32_bf16 v[94:97], v[152:155], v[222:225], v[94:97]
	v_mfma_f32_16x16x32_bf16 v[90:93], v[164:167], v[222:225], v[90:93]
	v_mfma_f32_16x16x32_bf16 v[78:81], v[152:155], v[230:233], v[78:81]
	v_mfma_f32_16x16x32_bf16 v[74:77], v[164:167], v[230:233], v[74:77]
	v_mfma_f32_16x16x32_bf16 v[126:129], v[160:163], v[206:209], v[126:129]
	v_mfma_f32_16x16x32_bf16 v[122:125], v[182:185], v[206:209], v[122:125]
	v_mfma_f32_16x16x32_bf16 v[110:113], v[160:163], v[218:221], v[110:113]
	v_mfma_f32_16x16x32_bf16 v[106:109], v[182:185], v[218:221], v[106:109]
	v_mfma_f32_16x16x32_bf16 v[94:97], v[160:163], v[226:229], v[94:97]
	v_mfma_f32_16x16x32_bf16 v[90:93], v[182:185], v[226:229], v[90:93]
	v_mfma_f32_16x16x32_bf16 v[78:81], v[160:163], v[234:237], v[78:81]
	v_mfma_f32_16x16x32_bf16 v[74:77], v[182:185], v[234:237], v[74:77]
	s_setprio 0
	s_setprio 1
	v_mfma_f32_16x16x32_bf16 v[118:121], v[186:189], v[202:205], v[118:121]
	v_mfma_f32_16x16x32_bf16 v[114:117], v[194:197], v[202:205], v[114:117]
	v_mfma_f32_16x16x32_bf16 v[102:105], v[186:189], v[214:217], v[102:105]
	v_mfma_f32_16x16x32_bf16 v[98:101], v[194:197], v[214:217], v[98:101]
	v_mfma_f32_16x16x32_bf16 v[86:89], v[186:189], v[222:225], v[86:89]
	v_mfma_f32_16x16x32_bf16 v[82:85], v[194:197], v[222:225], v[82:85]
	v_mfma_f32_16x16x32_bf16 v[70:73], v[186:189], v[230:233], v[70:73]
	v_mfma_f32_16x16x32_bf16 v[66:69], v[194:197], v[230:233], v[66:69]
	v_mfma_f32_16x16x32_bf16 v[118:121], v[190:193], v[206:209], v[118:121]
	v_mfma_f32_16x16x32_bf16 v[114:117], v[198:201], v[206:209], v[114:117]
	v_mfma_f32_16x16x32_bf16 v[102:105], v[190:193], v[218:221], v[102:105]
	v_mfma_f32_16x16x32_bf16 v[98:101], v[198:201], v[218:221], v[98:101]
	v_mfma_f32_16x16x32_bf16 v[86:89], v[190:193], v[226:229], v[86:89]
	v_mfma_f32_16x16x32_bf16 v[82:85], v[198:201], v[226:229], v[82:85]
	v_mfma_f32_16x16x32_bf16 v[70:73], v[190:193], v[234:237], v[70:73]
	v_mfma_f32_16x16x32_bf16 v[66:69], v[198:201], v[234:237], v[66:69]
	s_setprio 0
	s_barrier
	s_add_i32 s86, s86, s68
	v_lshl_add_u64 v[142:143], s[62:63], 0, v[0:1]
	s_mov_b32 m0, s86
	ds_read_b128 v[202:205], v158 offset:16384
	ds_read_b128 v[206:209], v158 offset:17408
	ds_read_b128 v[214:217], v158 offset:18432
	ds_read_b128 v[218:221], v158 offset:19456
	ds_read_b128 v[222:225], v158 offset:20480
	ds_read_b128 v[226:229], v158 offset:21504
	ds_read_b128 v[230:233], v158 offset:22528
	ds_read_b128 v[234:237], v158 offset:23552
	global_load_lds_dwordx4 v[142:143], off
	s_add_i32 m0, s86, 0x2000
	s_add_u32 s86, s62, 0x80000
	v_lshl_add_u64 v[144:145], s[62:63], 0, v[130:131]
	s_addc_u32 s87, s63, 0
	s_add_i32 s88, s88, s68
	global_load_lds_dwordx4 v[144:145], off
	v_lshl_add_u64 v[168:169], s[86:87], 0, v[0:1]
	s_mov_b32 m0, s88
	v_lshl_add_u64 v[238:239], s[64:65], 0, v[132:133]
	global_load_lds_dwordx4 v[168:169], off
	v_lshl_add_u64 v[168:169], s[86:87], 0, v[130:131]
	s_add_i32 m0, s88, 0x2000
	s_nop 0
	global_load_lds_dwordx4 v[168:169], off
	v_lshl_add_u64 v[168:169], s[64:65], 0, v[134:135]
	s_mov_b32 m0, s69
	s_nop 0
	global_load_lds_dwordx4 v[168:169], off
	s_mov_b32 m0, s70
	s_nop 0
	global_load_lds_dwordx4 v[238:239], off
	s_waitcnt vmcnt(8)
	s_waitcnt lgkmcnt(0)
	s_setprio 1
	s_barrier
; #define PG8_STAGE(bufoff, gbase, voff) do { _Pragma("unroll") for (int _i = 0; _i < 2; ++_i) \
;         __builtin_amdgcn_global_load_lds((const unsigned*)((const char*)(gbase) + (voff)[_i]), (PG8_LAS unsigned*)(lds + (bufoff) + ldsw + _i * 8192), 16, 0, 0); } while (0)
; #define PG8_LDA(dst, b, h) do { _Pragma("unroll") for (int m = 0; m < 4; ++m) _Pragma("unroll") for (int k = 0; k < 2; ++k) dst[m][k] = *(const PG8_LAS bf16x8*)(lds + PG8_SA(b, h) + aoff + m * 2048 + k * 1024); } while (0)
; #define PG8_LDB(dst, b, h) do { _Pragma("unroll") for (int n = 0; n < 2; ++n) _Pragma("unroll") for (int k = 0; k < 2; ++k) dst[n][k] = *(const PG8_LAS bf16x8*)(lds + PG8_SB(b, h) + boff + n * 2048 + k * 1024); } while (0)
; #define PG8_MMA(ai, bj, At, Bt) do { __builtin_amdgcn_s_setprio(1); _Pragma("unroll") for (int m = 0; m < 4; ++m) _Pragma("unroll") for (int n = 0; n < 2; ++n) _Pragma("unroll") for (int k = 0; k < 2; ++k) \
;         acc[ai][bj][m][n] = __builtin_amdgcn_mfma_f32_16x16x32_bf16(Bt[n][k], At[m][k], acc[ai][bj][m][n], 0, 0, 0); __builtin_amdgcn_s_setprio(0); } while (0)
; #define PG8_WAIT_V(n) asm volatile("s_waitcnt vmcnt(" #n ")" ::: "memory")
; #define PG8_WAIT_L(n) asm volatile("s_waitcnt lgkmcnt(" #n ")" ::: "memory")
; #define PG8_BAR __builtin_amdgcn_s_barrier()
; #define PG8_SCHED __builtin_amdgcn_sched_barrier(0)
; template <class Epi, class Sched, bool ALIGN_EPI = false, bool SP2 = false>
; __device__ __forceinline__ void gemm_phase(PG8_LAS unsigned char* lds, const Gemm g, const Sched& S, const Epi& E) {
;     ...
;             PG8_WAIT_V(8); PG8_WAIT_L(0); PG8_BAR; PG8_MMA(1, 0, At, B0); PG8_MMA(1, 1, At, B1); PG8_BAR; PG8_SCHED;
;             PG8_LDB(B0, 1, 0); PG8_LDB(B1, 1, 1); PG8_SCHED; PG8_LDA(At, 1, 0); PG8_STAGE(PG8_SA(0, 1), a2 + hstep, voffA);
;             PG8_WAIT_V(8); PG8_WAIT_L(0); PG8_BAR; PG8_MMA(0, 0, At, B0); PG8_MMA(0, 1, At, B1); PG8_BAR; PG8_SCHED;
;             PG8_LDA(At, 1, 1); PG8_STAGE(PG8_SB(1, 0), b3, voffB); PG8_STAGE(PG8_SB(1, 1), b3 + hstep, voffB); PG8_STAGE(PG8_SA(1, 0), a3, voffA);
	v_mfma_f32_16x16x32_bf16 v[62:65], v[152:155], v[202:205], v[62:65]
	v_mfma_f32_16x16x32_bf16 v[58:61], v[164:167], v[202:205], v[58:61]
	v_mfma_f32_16x16x32_bf16 v[46:49], v[152:155], v[214:217], v[46:49]
	v_mfma_f32_16x16x32_bf16 v[42:45], v[164:167], v[214:217], v[42:45]
	v_mfma_f32_16x16x32_bf16 v[30:33], v[152:155], v[222:225], v[30:33]
	v_mfma_f32_16x16x32_bf16 v[26:29], v[164:167], v[222:225], v[26:29]
	v_mfma_f32_16x16x32_bf16 v[14:17], v[152:155], v[230:233], v[14:17]
	v_mfma_f32_16x16x32_bf16 v[10:13], v[164:167], v[230:233], v[10:13]
	v_mfma_f32_16x16x32_bf16 v[62:65], v[160:163], v[206:209], v[62:65]
	v_mfma_f32_16x16x32_bf16 v[58:61], v[182:185], v[206:209], v[58:61]
	v_mfma_f32_16x16x32_bf16 v[46:49], v[160:163], v[218:221], v[46:49]
	v_mfma_f32_16x16x32_bf16 v[42:45], v[182:185], v[218:221], v[42:45]
	v_mfma_f32_16x16x32_bf16 v[30:33], v[160:163], v[226:229], v[30:33]
	v_mfma_f32_16x16x32_bf16 v[26:29], v[182:185], v[226:229], v[26:29]
	v_mfma_f32_16x16x32_bf16 v[14:17], v[160:163], v[234:237], v[14:17]
	v_mfma_f32_16x16x32_bf16 v[10:13], v[182:185], v[234:237], v[10:13]
	s_setprio 0
	s_setprio 1
	v_mfma_f32_16x16x32_bf16 v[54:57], v[186:189], v[202:205], v[54:57]
	v_mfma_f32_16x16x32_bf16 v[50:53], v[194:197], v[202:205], v[50:53]
	v_mfma_f32_16x16x32_bf16 v[38:41], v[186:189], v[214:217], v[38:41]
	v_mfma_f32_16x16x32_bf16 v[34:37], v[194:197], v[214:217], v[34:37]
	v_mfma_f32_16x16x32_bf16 v[22:25], v[186:189], v[222:225], v[22:25]
	v_mfma_f32_16x16x32_bf16 v[18:21], v[194:197], v[222:225], v[18:21]
	v_mfma_f32_16x16x32_bf16 v[6:9], v[186:189], v[230:233], v[6:9]
	v_mfma_f32_16x16x32_bf16 v[2:5], v[194:197], v[230:233], v[2:5]
	v_mfma_f32_16x16x32_bf16 v[54:57], v[190:193], v[206:209], v[54:57]
	v_mfma_f32_16x16x32_bf16 v[50:53], v[198:201], v[206:209], v[50:53]
	v_mfma_f32_16x16x32_bf16 v[38:41], v[190:193], v[218:221], v[38:41]
	v_mfma_f32_16x16x32_bf16 v[34:37], v[198:201], v[218:221], v[34:37]
	v_mfma_f32_16x16x32_bf16 v[22:25], v[190:193], v[226:229], v[22:25]
	v_mfma_f32_16x16x32_bf16 v[18:21], v[198:201], v[226:229], v[18:21]
	v_mfma_f32_16x16x32_bf16 v[6:9], v[190:193], v[234:237], v[6:9]
	v_mfma_f32_16x16x32_bf16 v[2:5], v[198:201], v[234:237], v[2:5]
	s_setprio 0
	s_barrier
	s_add_i32 s86, 0, 0x18000
	v_add_u32_e32 v159, s86, v156
	s_add_i32 s87, 0, 0x1c000
	ds_read_b128 v[152:155], v159
	ds_read_b128 v[160:163], v159 offset:1024
	ds_read_b128 v[164:167], v159 offset:2048
	ds_read_b128 v[182:185], v159 offset:3072
	v_add_u32_e32 v159, s87, v156
	ds_read_b128 v[186:189], v159
	ds_read_b128 v[190:193], v159 offset:1024
	ds_read_b128 v[194:197], v159 offset:2048
	ds_read_b128 v[198:201], v159 offset:3072
	s_add_u32 s64, s64, 0x80000
	s_addc_u32 s65, s65, 0
	s_mov_b32 m0, s71
	v_lshl_add_u64 v[240:241], s[64:65], 0, v[134:135]
	ds_read_b128 v[202:205], v158 offset:32768
	ds_read_b128 v[206:209], v158 offset:33792
	ds_read_b128 v[214:217], v158 offset:34816
	ds_read_b128 v[218:221], v158 offset:35840
	ds_read_b128 v[222:225], v158 offset:36864
	ds_read_b128 v[226:229], v158 offset:37888
	ds_read_b128 v[230:233], v158 offset:38912
	ds_read_b128 v[234:237], v158 offset:39936
	global_load_lds_dwordx4 v[240:241], off
	v_lshl_add_u64 v[240:241], s[64:65], 0, v[132:133]
	s_mov_b32 m0, s72
	s_nop 0
	global_load_lds_dwordx4 v[240:241], off
	s_waitcnt vmcnt(8)
	s_waitcnt lgkmcnt(0)
	s_setprio 1
	s_barrier
	v_mfma_f32_16x16x32_bf16 v[126:129], v[152:155], v[202:205], v[126:129]
	v_mfma_f32_16x16x32_bf16 v[122:125], v[164:167], v[202:205], v[122:125]
	v_mfma_f32_16x16x32_bf16 v[110:113], v[152:155], v[214:217], v[110:113]
	v_mfma_f32_16x16x32_bf16 v[106:109], v[164:167], v[214:217], v[106:109]
	v_mfma_f32_16x16x32_bf16 v[94:97], v[152:155], v[222:225], v[94:97]
	v_mfma_f32_16x16x32_bf16 v[90:93], v[164:167], v[222:225], v[90:93]
	v_mfma_f32_16x16x32_bf16 v[78:81], v[152:155], v[230:233], v[78:81]
	v_mfma_f32_16x16x32_bf16 v[74:77], v[164:167], v[230:233], v[74:77]
	v_mfma_f32_16x16x32_bf16 v[126:129], v[160:163], v[206:209], v[126:129]
	v_mfma_f32_16x16x32_bf16 v[122:125], v[182:185], v[206:209], v[122:125]
	v_mfma_f32_16x16x32_bf16 v[110:113], v[160:163], v[218:221], v[110:113]
	v_mfma_f32_16x16x32_bf16 v[106:109], v[182:185], v[218:221], v[106:109]
	v_mfma_f32_16x16x32_bf16 v[94:97], v[160:163], v[226:229], v[94:97]
	v_mfma_f32_16x16x32_bf16 v[90:93], v[182:185], v[226:229], v[90:93]
	v_mfma_f32_16x16x32_bf16 v[78:81], v[160:163], v[234:237], v[78:81]
	v_mfma_f32_16x16x32_bf16 v[74:77], v[182:185], v[234:237], v[74:77]
	s_setprio 0
	s_setprio 1
	v_mfma_f32_16x16x32_bf16 v[118:121], v[186:189], v[202:205], v[118:121]
	v_mfma_f32_16x16x32_bf16 v[114:117], v[194:197], v[202:205], v[114:117]
	v_mfma_f32_16x16x32_bf16 v[102:105], v[186:189], v[214:217], v[102:105]
	v_mfma_f32_16x16x32_bf16 v[98:101], v[194:197], v[214:217], v[98:101]
	v_mfma_f32_16x16x32_bf16 v[86:89], v[186:189], v[222:225], v[86:89]
	v_mfma_f32_16x16x32_bf16 v[82:85], v[194:197], v[222:225], v[82:85]
	v_mfma_f32_16x16x32_bf16 v[70:73], v[186:189], v[230:233], v[70:73]
	v_mfma_f32_16x16x32_bf16 v[66:69], v[194:197], v[230:233], v[66:69]
	v_mfma_f32_16x16x32_bf16 v[118:121], v[190:193], v[206:209], v[118:121]
	v_mfma_f32_16x16x32_bf16 v[114:117], v[198:201], v[206:209], v[114:117]
	v_mfma_f32_16x16x32_bf16 v[102:105], v[190:193], v[218:221], v[102:105]
	v_mfma_f32_16x16x32_bf16 v[98:101], v[198:201], v[218:221], v[98:101]
	v_mfma_f32_16x16x32_bf16 v[86:89], v[190:193], v[226:229], v[86:89]
	v_mfma_f32_16x16x32_bf16 v[82:85], v[198:201], v[226:229], v[82:85]
	v_mfma_f32_16x16x32_bf16 v[70:73], v[190:193], v[234:237], v[70:73]
	v_mfma_f32_16x16x32_bf16 v[66:69], v[198:201], v[234:237], v[66:69]
	s_setprio 0
	s_barrier
; #define PG8_STAGE(bufoff, gbase, voff) do { _Pragma("unroll") for (int _i = 0; _i < 2; ++_i) \
;         __builtin_amdgcn_global_load_lds((const unsigned*)((const char*)(gbase) + (voff)[_i]), (PG8_LAS unsigned*)(lds + (bufoff) + ldsw + _i * 8192), 16, 0, 0); } while (0)
; #define PG8_LDA(dst, b, h) do { _Pragma("unroll") for (int m = 0; m < 4; ++m) _Pragma("unroll") for (int k = 0; k < 2; ++k) dst[m][k] = *(const PG8_LAS bf16x8*)(lds + PG8_SA(b, h) + aoff + m * 2048 + k * 1024); } while (0)
; #define PG8_MMA(ai, bj, At, Bt) do { __builtin_amdgcn_s_setprio(1); _Pragma("unroll") for (int m = 0; m < 4; ++m) _Pragma("unroll") for (int n = 0; n < 2; ++n) _Pragma("unroll") for (int k = 0; k < 2; ++k) \
;         acc[ai][bj][m][n] = __builtin_amdgcn_mfma_f32_16x16x32_bf16(Bt[n][k], At[m][k], acc[ai][bj][m][n], 0, 0, 0); __builtin_amdgcn_s_setprio(0); } while (0)
; #define PG8_WAIT_V(n) asm volatile("s_waitcnt vmcnt(" #n ")" ::: "memory")
; #define PG8_WAIT_L(n) asm volatile("s_waitcnt lgkmcnt(" #n ")" ::: "memory")
; #define PG8_BAR __builtin_amdgcn_s_barrier()
; #define PG8_SCHED __builtin_amdgcn_sched_barrier(0)
; template <class Epi, class Sched, bool ALIGN_EPI = false, bool SP2 = false>
; __device__ __forceinline__ void gemm_phase(PG8_LAS unsigned char* lds, const Gemm g, const Sched& S, const Epi& E) {
;     ...
;             PG8_WAIT_V(8); PG8_WAIT_L(0); PG8_BAR; PG8_MMA(0, 0, At, B0); PG8_MMA(0, 1, At, B1); PG8_BAR; PG8_SCHED;
;             PG8_LDA(At, 1, 1); PG8_STAGE(PG8_SB(1, 0), b3, voffB); PG8_STAGE(PG8_SB(1, 1), b3 + hstep, voffB); PG8_STAGE(PG8_SA(1, 0), a3, voffA);
;             PG8_WAIT_V(8); PG8_WAIT_L(0); PG8_BAR; PG8_MMA(1, 0, At, B0); PG8_MMA(1, 1, At, B1); PG8_BAR; PG8_SCHED;
	s_add_i32 s64, s86, s68
	v_lshl_add_u64 v[142:143], v[142:143], 0, s[34:35]
	s_mov_b32 m0, s64
	ds_read_b128 v[202:205], v158 offset:49152
	ds_read_b128 v[206:209], v158 offset:50176
	ds_read_b128 v[214:217], v158 offset:51200
	ds_read_b128 v[218:221], v158 offset:52224
	ds_read_b128 v[222:225], v158 offset:53248
	ds_read_b128 v[226:229], v158 offset:54272
	ds_read_b128 v[230:233], v158 offset:55296
	ds_read_b128 v[234:237], v158 offset:56320
	global_load_lds_dwordx4 v[142:143], off
	s_add_i32 m0, s64, 0x2000
	s_add_u32 s62, s62, 0x80080
	v_lshl_add_u64 v[142:143], v[144:145], 0, s[34:35]
	s_addc_u32 s63, s63, 0
	s_add_i32 s64, s87, s68
	global_load_lds_dwordx4 v[142:143], off
	v_lshl_add_u64 v[142:143], s[62:63], 0, v[0:1]
	s_mov_b32 m0, s64
	s_nop 0
	global_load_lds_dwordx4 v[142:143], off
	v_lshl_add_u64 v[142:143], s[62:63], 0, v[130:131]
	s_add_i32 m0, s64, 0x2000
	s_nop 0
	global_load_lds_dwordx4 v[142:143], off
	v_lshl_add_u64 v[142:143], v[168:169], 0, s[34:35]
	s_mov_b32 m0, s74
	s_nop 0
	global_load_lds_dwordx4 v[142:143], off
	v_lshl_add_u64 v[142:143], v[238:239], 0, s[34:35]
	s_mov_b32 m0, s75
	s_nop 0
	global_load_lds_dwordx4 v[142:143], off
	s_waitcnt vmcnt(8)
	s_waitcnt lgkmcnt(0)
	s_setprio 1
	s_barrier
	v_mfma_f32_16x16x32_bf16 v[62:65], v[152:155], v[202:205], v[62:65]
	v_mfma_f32_16x16x32_bf16 v[58:61], v[164:167], v[202:205], v[58:61]
	v_mfma_f32_16x16x32_bf16 v[46:49], v[152:155], v[214:217], v[46:49]
	v_mfma_f32_16x16x32_bf16 v[42:45], v[164:167], v[214:217], v[42:45]
	v_mfma_f32_16x16x32_bf16 v[30:33], v[152:155], v[222:225], v[30:33]
	v_mfma_f32_16x16x32_bf16 v[26:29], v[164:167], v[222:225], v[26:29]
	v_mfma_f32_16x16x32_bf16 v[14:17], v[152:155], v[230:233], v[14:17]
	v_mfma_f32_16x16x32_bf16 v[10:13], v[164:167], v[230:233], v[10:13]
	v_mfma_f32_16x16x32_bf16 v[62:65], v[160:163], v[206:209], v[62:65]
	v_mfma_f32_16x16x32_bf16 v[58:61], v[182:185], v[206:209], v[58:61]
	v_mfma_f32_16x16x32_bf16 v[46:49], v[160:163], v[218:221], v[46:49]
	v_mfma_f32_16x16x32_bf16 v[42:45], v[182:185], v[218:221], v[42:45]
	v_mfma_f32_16x16x32_bf16 v[30:33], v[160:163], v[226:229], v[30:33]
	v_mfma_f32_16x16x32_bf16 v[26:29], v[182:185], v[226:229], v[26:29]
	v_mfma_f32_16x16x32_bf16 v[14:17], v[160:163], v[234:237], v[14:17]
	v_mfma_f32_16x16x32_bf16 v[10:13], v[182:185], v[234:237], v[10:13]
	s_setprio 0
	s_setprio 1
	v_mfma_f32_16x16x32_bf16 v[54:57], v[186:189], v[202:205], v[54:57]
	v_mfma_f32_16x16x32_bf16 v[50:53], v[194:197], v[202:205], v[50:53]
	v_mfma_f32_16x16x32_bf16 v[38:41], v[186:189], v[214:217], v[38:41]
	v_mfma_f32_16x16x32_bf16 v[34:37], v[194:197], v[214:217], v[34:37]
	v_mfma_f32_16x16x32_bf16 v[22:25], v[186:189], v[222:225], v[22:25]
	v_mfma_f32_16x16x32_bf16 v[18:21], v[194:197], v[222:225], v[18:21]
	v_mfma_f32_16x16x32_bf16 v[6:9], v[186:189], v[230:233], v[6:9]
	v_mfma_f32_16x16x32_bf16 v[2:5], v[194:197], v[230:233], v[2:5]
	v_mfma_f32_16x16x32_bf16 v[54:57], v[190:193], v[206:209], v[54:57]
	v_mfma_f32_16x16x32_bf16 v[50:53], v[198:201], v[206:209], v[50:53]
	v_mfma_f32_16x16x32_bf16 v[38:41], v[190:193], v[218:221], v[38:41]
	v_mfma_f32_16x16x32_bf16 v[34:37], v[198:201], v[218:221], v[34:37]
	v_mfma_f32_16x16x32_bf16 v[22:25], v[190:193], v[226:229], v[22:25]
	v_mfma_f32_16x16x32_bf16 v[18:21], v[198:201], v[226:229], v[18:21]
	v_mfma_f32_16x16x32_bf16 v[6:9], v[190:193], v[234:237], v[6:9]
	v_mfma_f32_16x16x32_bf16 v[2:5], v[198:201], v[234:237], v[2:5]
	s_setprio 0
	s_barrier
	s_add_i32 s83, s83, 2
	s_add_u32 s79, s79, 0x100
	s_addc_u32 s82, s82, 0
	s_add_u32 s60, s60, 0x100
	s_addc_u32 s61, s61, 0
	s_cmp_gt_u32 s83, 29
	s_cbranch_scc0 .LBB0_38
	s_and_b64 vcc, exec, s[50:51]
	s_cbranch_vccz .LBB0_41
	s_barrier

; #define PG8_STAGE(bufoff, gbase, voff) do { _Pragma("unroll") for (int _i = 0; _i < 2; ++_i) \
;         __builtin_amdgcn_global_load_lds((const unsigned*)((const char*)(gbase) + (voff)[_i]), (PG8_LAS unsigned*)(lds + (bufoff) + ldsw + _i * 8192), 16, 0, 0); } while (0)
; #define PG8_LDA(dst, b, h) do { _Pragma("unroll") for (int m = 0; m < 4; ++m) _Pragma("unroll") for (int k = 0; k < 2; ++k) dst[m][k] = *(const PG8_LAS bf16x8*)(lds + PG8_SA(b, h) + aoff + m * 2048 + k * 1024); } while (0)
; #define PG8_LDB(dst, b, h) do { _Pragma("unroll") for (int n = 0; n < 2; ++n) _Pragma("unroll") for (int k = 0; k < 2; ++k) dst[n][k] = *(const PG8_LAS bf16x8*)(lds + PG8_SB(b, h) + boff + n * 2048 + k * 1024); } while (0)
; #define PG8_MMA(ai, bj, At, Bt) do { __builtin_amdgcn_s_setprio(1); _Pragma("unroll") for (int m = 0; m < 4; ++m) _Pragma("unroll") for (int n = 0; n < 2; ++n) _Pragma("unroll") for (int k = 0; k < 2; ++k) \
;         acc[ai][bj][m][n] = __builtin_amdgcn_mfma_f32_16x16x32_bf16(Bt[n][k], At[m][k], acc[ai][bj][m][n], 0, 0, 0); __builtin_amdgcn_s_setprio(0); } while (0)
; #define PG8_WAIT_V(n) asm volatile("s_waitcnt vmcnt(" #n ")" ::: "memory")
; #define PG8_WAIT_L(n) asm volatile("s_waitcnt lgkmcnt(" #n ")" ::: "memory")
; #define PG8_BAR __builtin_amdgcn_s_barrier()
; #define PG8_SCHED __builtin_amdgcn_sched_barrier(0)
; template <class Epi, class Sched, bool ALIGN_EPI = false, bool SP2 = false>
; __device__ __forceinline__ void gemm_phase(PG8_LAS unsigned char* lds, const Gemm g, const Sched& S, const Epi& E) {
;     ...
;             PG8_LDB(B0, 0, 0); PG8_LDB(B1, 0, 1); PG8_SCHED; PG8_LDA(At, 0, 0); PG8_STAGE(PG8_SA(1, 1), a1 + hstep, voffA);
;             PG8_WAIT_V(8); PG8_WAIT_L(0); PG8_BAR; PG8_MMA(0, 0, At, B0); PG8_MMA(0, 1, At, B1); PG8_BAR; PG8_SCHED;
;             PG8_LDA(At, 0, 1); PG8_STAGE(PG8_SB(0, 0), b2, voffB); PG8_STAGE(PG8_SB(0, 1), b2 + hstep, voffB); PG8_STAGE(PG8_SA(0, 0), a2, voffA);
;             PG8_WAIT_V(8); PG8_WAIT_L(0); PG8_BAR; PG8_MMA(1, 0, At, B0); PG8_MMA(1, 1, At, B1); PG8_BAR; PG8_SCHED;
;             PG8_LDB(B0, 1, 0); PG8_LDB(B1, 1, 1); PG8_SCHED; PG8_LDA(At, 1, 0); PG8_STAGE(PG8_SA(0, 1), a2 + hstep, voffA);
.LBB0_77:
	s_add_u32 s62, s58, s60
	s_addc_u32 s63, s59, s61
	s_add_u32 s62, s62, 0x100
	s_addc_u32 s63, s63, 0
	s_add_u32 s79, s76, s60
	s_addc_u32 s82, s77, s61
	s_cmpk_eq_i32 s60, 0xf00
	s_cselect_b32 s65, s2, s63
	s_cselect_b32 s64, s3, s62
	s_cselect_b32 s63, s51, s82
	s_cselect_b32 s62, s53, s79
	s_add_i32 s79, 0, 0x10000
	v_add_u32_e32 v142, s79, v182
	s_add_i32 s86, 0, 0x14000
	ds_read_b128 v[130:133], v142
	ds_read_b128 v[134:137], v142 offset:1024
	ds_read_b128 v[186:189], v142 offset:2048
	ds_read_b128 v[190:193], v142 offset:3072
	v_add_u32_e32 v142, s86, v182
	ds_read_b128 v[194:197], v142
	ds_read_b128 v[198:201], v142 offset:1024
	ds_read_b128 v[202:205], v142 offset:2048
	ds_read_b128 v[206:209], v142 offset:3072
	v_lshl_add_u64 v[168:169], v[166:167], 0, s[60:61]
	s_add_i32 m0, s69, 0xc000
	ds_read_b128 v[214:217], v184
	ds_read_b128 v[218:221], v184 offset:1024
	ds_read_b128 v[222:225], v184 offset:2048
	ds_read_b128 v[226:229], v184 offset:3072
	ds_read_b128 v[230:233], v184 offset:4096
	ds_read_b128 v[234:237], v184 offset:5120
	ds_read_b128 v[238:241], v184 offset:6144
	ds_read_b128 v[242:245], v184 offset:7168
	global_load_lds_dwordx4 v[168:169], off
	v_lshl_add_u64 v[168:169], v[164:165], 0, s[60:61]
	s_add_i32 m0, s69, 0xe000
	s_nop 0
	global_load_lds_dwordx4 v[168:169], off
	s_waitcnt vmcnt(8)
	s_waitcnt lgkmcnt(0)
	s_setprio 1
	s_barrier
	v_mfma_f32_16x16x32_bf16 v[126:129], v[130:133], v[214:217], v[126:129]
	v_mfma_f32_16x16x32_bf16 v[122:125], v[186:189], v[214:217], v[122:125]
	v_mfma_f32_16x16x32_bf16 v[110:113], v[130:133], v[222:225], v[110:113]
	v_mfma_f32_16x16x32_bf16 v[106:109], v[186:189], v[222:225], v[106:109]
	v_mfma_f32_16x16x32_bf16 v[94:97], v[130:133], v[230:233], v[94:97]
	v_mfma_f32_16x16x32_bf16 v[90:93], v[186:189], v[230:233], v[90:93]
	v_mfma_f32_16x16x32_bf16 v[78:81], v[130:133], v[238:241], v[78:81]
	v_mfma_f32_16x16x32_bf16 v[74:77], v[186:189], v[238:241], v[74:77]
	v_mfma_f32_16x16x32_bf16 v[126:129], v[134:137], v[218:221], v[126:129]
	v_mfma_f32_16x16x32_bf16 v[122:125], v[190:193], v[218:221], v[122:125]
	v_mfma_f32_16x16x32_bf16 v[110:113], v[134:137], v[226:229], v[110:113]
	v_mfma_f32_16x16x32_bf16 v[106:109], v[190:193], v[226:229], v[106:109]
	v_mfma_f32_16x16x32_bf16 v[94:97], v[134:137], v[234:237], v[94:97]
	v_mfma_f32_16x16x32_bf16 v[90:93], v[190:193], v[234:237], v[90:93]
	v_mfma_f32_16x16x32_bf16 v[78:81], v[134:137], v[242:245], v[78:81]
	v_mfma_f32_16x16x32_bf16 v[74:77], v[190:193], v[242:245], v[74:77]
	s_setprio 0
	s_setprio 1
	v_mfma_f32_16x16x32_bf16 v[118:121], v[194:197], v[214:217], v[118:121]
	v_mfma_f32_16x16x32_bf16 v[114:117], v[202:205], v[214:217], v[114:117]
	v_mfma_f32_16x16x32_bf16 v[102:105], v[194:197], v[222:225], v[102:105]
	v_mfma_f32_16x16x32_bf16 v[98:101], v[202:205], v[222:225], v[98:101]
	v_mfma_f32_16x16x32_bf16 v[86:89], v[194:197], v[230:233], v[86:89]
	v_mfma_f32_16x16x32_bf16 v[82:85], v[202:205], v[230:233], v[82:85]
	v_mfma_f32_16x16x32_bf16 v[70:73], v[194:197], v[238:241], v[70:73]
	v_mfma_f32_16x16x32_bf16 v[66:69], v[202:205], v[238:241], v[66:69]
	v_mfma_f32_16x16x32_bf16 v[118:121], v[198:201], v[218:221], v[118:121]
	v_mfma_f32_16x16x32_bf16 v[114:117], v[206:209], v[218:221], v[114:117]
	v_mfma_f32_16x16x32_bf16 v[102:105], v[198:201], v[226:229], v[102:105]
	v_mfma_f32_16x16x32_bf16 v[98:101], v[206:209], v[226:229], v[98:101]
	v_mfma_f32_16x16x32_bf16 v[86:89], v[198:201], v[234:237], v[86:89]
	v_mfma_f32_16x16x32_bf16 v[82:85], v[206:209], v[234:237], v[82:85]
	v_mfma_f32_16x16x32_bf16 v[70:73], v[198:201], v[242:245], v[70:73]
	v_mfma_f32_16x16x32_bf16 v[66:69], v[206:209], v[242:245], v[66:69]
	s_setprio 0
	s_barrier
	s_add_i32 s79, s79, s68
	v_lshl_add_u64 v[168:169], s[62:63], 0, v[0:1]
	s_mov_b32 m0, s79
	ds_read_b128 v[214:217], v184 offset:16384
	ds_read_b128 v[218:221], v184 offset:17408
	ds_read_b128 v[222:225], v184 offset:18432
	ds_read_b128 v[226:229], v184 offset:19456
	ds_read_b128 v[230:233], v184 offset:20480
	ds_read_b128 v[234:237], v184 offset:21504
	ds_read_b128 v[238:241], v184 offset:22528
	ds_read_b128 v[242:245], v184 offset:23552
	global_load_lds_dwordx4 v[168:169], off
	s_add_i32 m0, s79, 0x2000
	s_add_u32 s82, s62, 0x80000
	v_lshl_add_u64 v[246:247], s[62:63], 0, v[150:151]
	s_addc_u32 s83, s63, 0
	s_add_i32 s79, s86, s68
	global_load_lds_dwordx4 v[246:247], off
	v_lshl_add_u64 v[248:249], s[82:83], 0, v[0:1]
	s_mov_b32 m0, s79
	v_lshl_add_u64 v[142:143], s[64:65], 0, v[152:153]
	global_load_lds_dwordx4 v[248:249], off
	v_lshl_add_u64 v[248:249], s[82:83], 0, v[150:151]
	s_add_i32 m0, s79, 0x2000
	s_nop 0
	global_load_lds_dwordx4 v[248:249], off
	v_lshl_add_u64 v[248:249], s[64:65], 0, v[154:155]
	s_mov_b32 m0, s69
	s_nop 0
	global_load_lds_dwordx4 v[248:249], off
	s_mov_b32 m0, s70
	s_nop 0
	global_load_lds_dwordx4 v[142:143], off
	s_waitcnt vmcnt(8)
	s_waitcnt lgkmcnt(0)
	s_setprio 1
	s_barrier
; #define PG8_STAGE(bufoff, gbase, voff) do { _Pragma("unroll") for (int _i = 0; _i < 2; ++_i) \
;         __builtin_amdgcn_global_load_lds((const unsigned*)((const char*)(gbase) + (voff)[_i]), (PG8_LAS unsigned*)(lds + (bufoff) + ldsw + _i * 8192), 16, 0, 0); } while (0)
; #define PG8_LDA(dst, b, h) do { _Pragma("unroll") for (int m = 0; m < 4; ++m) _Pragma("unroll") for (int k = 0; k < 2; ++k) dst[m][k] = *(const PG8_LAS bf16x8*)(lds + PG8_SA(b, h) + aoff + m * 2048 + k * 1024); } while (0)
; #define PG8_LDB(dst, b, h) do { _Pragma("unroll") for (int n = 0; n < 2; ++n) _Pragma("unroll") for (int k = 0; k < 2; ++k) dst[n][k] = *(const PG8_LAS bf16x8*)(lds + PG8_SB(b, h) + boff + n * 2048 + k * 1024); } while (0)
; #define PG8_MMA(ai, bj, At, Bt) do { __builtin_amdgcn_s_setprio(1); _Pragma("unroll") for (int m = 0; m < 4; ++m) _Pragma("unroll") for (int n = 0; n < 2; ++n) _Pragma("unroll") for (int k = 0; k < 2; ++k) \
;         acc[ai][bj][m][n] = __builtin_amdgcn_mfma_f32_16x16x32_bf16(Bt[n][k], At[m][k], acc[ai][bj][m][n], 0, 0, 0); __builtin_amdgcn_s_setprio(0); } while (0)
; #define PG8_WAIT_V(n) asm volatile("s_waitcnt vmcnt(" #n ")" ::: "memory")
; #define PG8_WAIT_L(n) asm volatile("s_waitcnt lgkmcnt(" #n ")" ::: "memory")
; #define PG8_BAR __builtin_amdgcn_s_barrier()
; #define PG8_SCHED __builtin_amdgcn_sched_barrier(0)
; template <class Epi, class Sched, bool ALIGN_EPI = false, bool SP2 = false>
; __device__ __forceinline__ void gemm_phase(PG8_LAS unsigned char* lds, const Gemm g, const Sched& S, const Epi& E) {
;     ...
;             PG8_WAIT_V(8); PG8_WAIT_L(0); PG8_BAR; PG8_MMA(1, 0, At, B0); PG8_MMA(1, 1, At, B1); PG8_BAR; PG8_SCHED;
;             PG8_LDB(B0, 1, 0); PG8_LDB(B1, 1, 1); PG8_SCHED; PG8_LDA(At, 1, 0); PG8_STAGE(PG8_SA(0, 1), a2 + hstep, voffA);
;             PG8_WAIT_V(8); PG8_WAIT_L(0); PG8_BAR; PG8_MMA(0, 0, At, B0); PG8_MMA(0, 1, At, B1); PG8_BAR; PG8_SCHED;
;             PG8_LDA(At, 1, 1); PG8_STAGE(PG8_SB(1, 0), b3, voffB); PG8_STAGE(PG8_SB(1, 1), b3 + hstep, voffB); PG8_STAGE(PG8_SA(1, 0), a3, voffA);
	v_mfma_f32_16x16x32_bf16 v[62:65], v[130:133], v[214:217], v[62:65]
	v_mfma_f32_16x16x32_bf16 v[58:61], v[186:189], v[214:217], v[58:61]
	v_mfma_f32_16x16x32_bf16 v[46:49], v[130:133], v[222:225], v[46:49]
	v_mfma_f32_16x16x32_bf16 v[42:45], v[186:189], v[222:225], v[42:45]
	v_mfma_f32_16x16x32_bf16 v[30:33], v[130:133], v[230:233], v[30:33]
	v_mfma_f32_16x16x32_bf16 v[26:29], v[186:189], v[230:233], v[26:29]
	v_mfma_f32_16x16x32_bf16 v[14:17], v[130:133], v[238:241], v[14:17]
	v_mfma_f32_16x16x32_bf16 v[10:13], v[186:189], v[238:241], v[10:13]
	v_mfma_f32_16x16x32_bf16 v[62:65], v[134:137], v[218:221], v[62:65]
	v_mfma_f32_16x16x32_bf16 v[58:61], v[190:193], v[218:221], v[58:61]
	v_mfma_f32_16x16x32_bf16 v[46:49], v[134:137], v[226:229], v[46:49]
	v_mfma_f32_16x16x32_bf16 v[42:45], v[190:193], v[226:229], v[42:45]
	v_mfma_f32_16x16x32_bf16 v[30:33], v[134:137], v[234:237], v[30:33]
	v_mfma_f32_16x16x32_bf16 v[26:29], v[190:193], v[234:237], v[26:29]
	v_mfma_f32_16x16x32_bf16 v[14:17], v[134:137], v[242:245], v[14:17]
	v_mfma_f32_16x16x32_bf16 v[10:13], v[190:193], v[242:245], v[10:13]
	s_setprio 0
	s_setprio 1
	v_mfma_f32_16x16x32_bf16 v[54:57], v[194:197], v[214:217], v[54:57]
	v_mfma_f32_16x16x32_bf16 v[50:53], v[202:205], v[214:217], v[50:53]
	v_mfma_f32_16x16x32_bf16 v[38:41], v[194:197], v[222:225], v[38:41]
	v_mfma_f32_16x16x32_bf16 v[34:37], v[202:205], v[222:225], v[34:37]
	v_mfma_f32_16x16x32_bf16 v[22:25], v[194:197], v[230:233], v[22:25]
	v_mfma_f32_16x16x32_bf16 v[18:21], v[202:205], v[230:233], v[18:21]
	v_mfma_f32_16x16x32_bf16 v[6:9], v[194:197], v[238:241], v[6:9]
	v_mfma_f32_16x16x32_bf16 v[2:5], v[202:205], v[238:241], v[2:5]
	v_mfma_f32_16x16x32_bf16 v[54:57], v[198:201], v[218:221], v[54:57]
	v_mfma_f32_16x16x32_bf16 v[50:53], v[206:209], v[218:221], v[50:53]
	v_mfma_f32_16x16x32_bf16 v[38:41], v[198:201], v[226:229], v[38:41]
	v_mfma_f32_16x16x32_bf16 v[34:37], v[206:209], v[226:229], v[34:37]
	v_mfma_f32_16x16x32_bf16 v[22:25], v[198:201], v[234:237], v[22:25]
	v_mfma_f32_16x16x32_bf16 v[18:21], v[206:209], v[234:237], v[18:21]
	v_mfma_f32_16x16x32_bf16 v[6:9], v[198:201], v[242:245], v[6:9]
	v_mfma_f32_16x16x32_bf16 v[2:5], v[206:209], v[242:245], v[2:5]
	s_setprio 0
	s_barrier
	s_add_i32 s79, 0, 0x18000
	v_add_u32_e32 v144, s79, v182
	s_add_i32 s82, 0, 0x1c000
	ds_read_b128 v[130:133], v144
	ds_read_b128 v[134:137], v144 offset:1024
	ds_read_b128 v[186:189], v144 offset:2048
	ds_read_b128 v[190:193], v144 offset:3072
	v_add_u32_e32 v144, s82, v182
	ds_read_b128 v[194:197], v144
	ds_read_b128 v[198:201], v144 offset:1024
	ds_read_b128 v[202:205], v144 offset:2048
	ds_read_b128 v[206:209], v144 offset:3072
	s_add_u32 s64, s64, 0x80000
	s_addc_u32 s65, s65, 0
	s_mov_b32 m0, s71
	v_lshl_add_u64 v[144:145], s[64:65], 0, v[154:155]
	ds_read_b128 v[214:217], v184 offset:32768
	ds_read_b128 v[218:221], v184 offset:33792
	ds_read_b128 v[222:225], v184 offset:34816
	ds_read_b128 v[226:229], v184 offset:35840
	ds_read_b128 v[230:233], v184 offset:36864
	ds_read_b128 v[234:237], v184 offset:37888
	ds_read_b128 v[238:241], v184 offset:38912
	ds_read_b128 v[242:245], v184 offset:39936
	global_load_lds_dwordx4 v[144:145], off
	v_lshl_add_u64 v[144:145], s[64:65], 0, v[152:153]
	s_mov_b32 m0, s72
	s_nop 0
	global_load_lds_dwordx4 v[144:145], off
	s_waitcnt vmcnt(8)
	s_waitcnt lgkmcnt(0)
	s_setprio 1
	s_barrier
	v_mfma_f32_16x16x32_bf16 v[126:129], v[130:133], v[214:217], v[126:129]
	v_mfma_f32_16x16x32_bf16 v[122:125], v[186:189], v[214:217], v[122:125]
	v_mfma_f32_16x16x32_bf16 v[110:113], v[130:133], v[222:225], v[110:113]
	v_mfma_f32_16x16x32_bf16 v[106:109], v[186:189], v[222:225], v[106:109]
	v_mfma_f32_16x16x32_bf16 v[94:97], v[130:133], v[230:233], v[94:97]
	v_mfma_f32_16x16x32_bf16 v[90:93], v[186:189], v[230:233], v[90:93]
	v_mfma_f32_16x16x32_bf16 v[78:81], v[130:133], v[238:241], v[78:81]
	v_mfma_f32_16x16x32_bf16 v[74:77], v[186:189], v[238:241], v[74:77]
	v_mfma_f32_16x16x32_bf16 v[126:129], v[134:137], v[218:221], v[126:129]
	v_mfma_f32_16x16x32_bf16 v[122:125], v[190:193], v[218:221], v[122:125]
	v_mfma_f32_16x16x32_bf16 v[110:113], v[134:137], v[226:229], v[110:113]
	v_mfma_f32_16x16x32_bf16 v[106:109], v[190:193], v[226:229], v[106:109]
	v_mfma_f32_16x16x32_bf16 v[94:97], v[134:137], v[234:237], v[94:97]
	v_mfma_f32_16x16x32_bf16 v[90:93], v[190:193], v[234:237], v[90:93]
	v_mfma_f32_16x16x32_bf16 v[78:81], v[134:137], v[242:245], v[78:81]
	v_mfma_f32_16x16x32_bf16 v[74:77], v[190:193], v[242:245], v[74:77]
	s_setprio 0
	s_setprio 1
	v_mfma_f32_16x16x32_bf16 v[118:121], v[194:197], v[214:217], v[118:121]
	v_mfma_f32_16x16x32_bf16 v[114:117], v[202:205], v[214:217], v[114:117]
	v_mfma_f32_16x16x32_bf16 v[102:105], v[194:197], v[222:225], v[102:105]
	v_mfma_f32_16x16x32_bf16 v[98:101], v[202:205], v[222:225], v[98:101]
	v_mfma_f32_16x16x32_bf16 v[86:89], v[194:197], v[230:233], v[86:89]
	v_mfma_f32_16x16x32_bf16 v[82:85], v[202:205], v[230:233], v[82:85]
	v_mfma_f32_16x16x32_bf16 v[70:73], v[194:197], v[238:241], v[70:73]
	v_mfma_f32_16x16x32_bf16 v[66:69], v[202:205], v[238:241], v[66:69]
	v_mfma_f32_16x16x32_bf16 v[118:121], v[198:201], v[218:221], v[118:121]
	v_mfma_f32_16x16x32_bf16 v[114:117], v[206:209], v[218:221], v[114:117]
	v_mfma_f32_16x16x32_bf16 v[102:105], v[198:201], v[226:229], v[102:105]
	v_mfma_f32_16x16x32_bf16 v[98:101], v[206:209], v[226:229], v[98:101]
	v_mfma_f32_16x16x32_bf16 v[86:89], v[198:201], v[234:237], v[86:89]
	v_mfma_f32_16x16x32_bf16 v[82:85], v[206:209], v[234:237], v[82:85]
	v_mfma_f32_16x16x32_bf16 v[70:73], v[198:201], v[242:245], v[70:73]
	v_mfma_f32_16x16x32_bf16 v[66:69], v[206:209], v[242:245], v[66:69]
	s_setprio 0
	s_barrier
; #define PG8_STAGE(bufoff, gbase, voff) do { _Pragma("unroll") for (int _i = 0; _i < 2; ++_i) \
;         __builtin_amdgcn_global_load_lds((const unsigned*)((const char*)(gbase) + (voff)[_i]), (PG8_LAS unsigned*)(lds + (bufoff) + ldsw + _i * 8192), 16, 0, 0); } while (0)
; #define PG8_LDA(dst, b, h) do { _Pragma("unroll") for (int m = 0; m < 4; ++m) _Pragma("unroll") for (int k = 0; k < 2; ++k) dst[m][k] = *(const PG8_LAS bf16x8*)(lds + PG8_SA(b, h) + aoff + m * 2048 + k * 1024); } while (0)
; #define PG8_MMA(ai, bj, At, Bt) do { __builtin_amdgcn_s_setprio(1); _Pragma("unroll") for (int m = 0; m < 4; ++m) _Pragma("unroll") for (int n = 0; n < 2; ++n) _Pragma("unroll") for (int k = 0; k < 2; ++k) \
;         acc[ai][bj][m][n] = __builtin_amdgcn_mfma_f32_16x16x32_bf16(Bt[n][k], At[m][k], acc[ai][bj][m][n], 0, 0, 0); __builtin_amdgcn_s_setprio(0); } while (0)
; #define PG8_WAIT_V(n) asm volatile("s_waitcnt vmcnt(" #n ")" ::: "memory")
; #define PG8_WAIT_L(n) asm volatile("s_waitcnt lgkmcnt(" #n ")" ::: "memory")
; #define PG8_BAR __builtin_amdgcn_s_barrier()
; #define PG8_SCHED __builtin_amdgcn_sched_barrier(0)
; template <class Epi, class Sched, bool ALIGN_EPI = false, bool SP2 = false>
; __device__ __forceinline__ void gemm_phase(PG8_LAS unsigned char* lds, const Gemm g, const Sched& S, const Epi& E) {
;     ...
;             PG8_WAIT_V(8); PG8_WAIT_L(0); PG8_BAR; PG8_MMA(0, 0, At, B0); PG8_MMA(0, 1, At, B1); PG8_BAR; PG8_SCHED;
;             PG8_LDA(At, 1, 1); PG8_STAGE(PG8_SB(1, 0), b3, voffB); PG8_STAGE(PG8_SB(1, 1), b3 + hstep, voffB); PG8_STAGE(PG8_SA(1, 0), a3, voffA);
;             PG8_WAIT_V(8); PG8_WAIT_L(0); PG8_BAR; PG8_MMA(1, 0, At, B0); PG8_MMA(1, 1, At, B1); PG8_BAR; PG8_SCHED;
	s_add_i32 s64, s79, s68
	v_lshl_add_u64 v[144:145], v[168:169], 0, s[34:35]
	s_mov_b32 m0, s64
	ds_read_b128 v[214:217], v184 offset:49152
	ds_read_b128 v[218:221], v184 offset:50176
	ds_read_b128 v[222:225], v184 offset:51200
	ds_read_b128 v[226:229], v184 offset:52224
	ds_read_b128 v[230:233], v184 offset:53248
	ds_read_b128 v[234:237], v184 offset:54272
	ds_read_b128 v[238:241], v184 offset:55296
	ds_read_b128 v[242:245], v184 offset:56320
	global_load_lds_dwordx4 v[144:145], off
	s_add_i32 m0, s64, 0x2000
	s_add_u32 s62, s62, 0x80080
	v_lshl_add_u64 v[144:145], v[246:247], 0, s[34:35]
	s_addc_u32 s63, s63, 0
	s_add_i32 s64, s82, s68
	global_load_lds_dwordx4 v[144:145], off
	v_lshl_add_u64 v[144:145], s[62:63], 0, v[0:1]
	s_mov_b32 m0, s64
	v_lshl_add_u64 v[142:143], v[142:143], 0, s[34:35]
	global_load_lds_dwordx4 v[144:145], off
	v_lshl_add_u64 v[144:145], s[62:63], 0, v[150:151]
	s_add_i32 m0, s64, 0x2000
	s_nop 0
	global_load_lds_dwordx4 v[144:145], off
	v_lshl_add_u64 v[144:145], v[248:249], 0, s[34:35]
	s_mov_b32 m0, s73
	s_nop 0
	global_load_lds_dwordx4 v[144:145], off
	s_mov_b32 m0, s74
	s_nop 0
	global_load_lds_dwordx4 v[142:143], off
	s_waitcnt vmcnt(8)
	s_waitcnt lgkmcnt(0)
	s_setprio 1
	s_barrier
	v_mfma_f32_16x16x32_bf16 v[62:65], v[130:133], v[214:217], v[62:65]
	v_mfma_f32_16x16x32_bf16 v[58:61], v[186:189], v[214:217], v[58:61]
	v_mfma_f32_16x16x32_bf16 v[46:49], v[130:133], v[222:225], v[46:49]
	v_mfma_f32_16x16x32_bf16 v[42:45], v[186:189], v[222:225], v[42:45]
	v_mfma_f32_16x16x32_bf16 v[30:33], v[130:133], v[230:233], v[30:33]
	v_mfma_f32_16x16x32_bf16 v[26:29], v[186:189], v[230:233], v[26:29]
	v_mfma_f32_16x16x32_bf16 v[14:17], v[130:133], v[238:241], v[14:17]
	v_mfma_f32_16x16x32_bf16 v[10:13], v[186:189], v[238:241], v[10:13]
	v_mfma_f32_16x16x32_bf16 v[62:65], v[134:137], v[218:221], v[62:65]
	v_mfma_f32_16x16x32_bf16 v[58:61], v[190:193], v[218:221], v[58:61]
	v_mfma_f32_16x16x32_bf16 v[46:49], v[134:137], v[226:229], v[46:49]
	v_mfma_f32_16x16x32_bf16 v[42:45], v[190:193], v[226:229], v[42:45]
	v_mfma_f32_16x16x32_bf16 v[30:33], v[134:137], v[234:237], v[30:33]
	v_mfma_f32_16x16x32_bf16 v[26:29], v[190:193], v[234:237], v[26:29]
	v_mfma_f32_16x16x32_bf16 v[14:17], v[134:137], v[242:245], v[14:17]
	v_mfma_f32_16x16x32_bf16 v[10:13], v[190:193], v[242:245], v[10:13]
	s_setprio 0
	s_setprio 1
	v_mfma_f32_16x16x32_bf16 v[54:57], v[194:197], v[214:217], v[54:57]
	v_mfma_f32_16x16x32_bf16 v[50:53], v[202:205], v[214:217], v[50:53]
	v_mfma_f32_16x16x32_bf16 v[38:41], v[194:197], v[222:225], v[38:41]
	v_mfma_f32_16x16x32_bf16 v[34:37], v[202:205], v[222:225], v[34:37]
	v_mfma_f32_16x16x32_bf16 v[22:25], v[194:197], v[230:233], v[22:25]
	v_mfma_f32_16x16x32_bf16 v[18:21], v[202:205], v[230:233], v[18:21]
	v_mfma_f32_16x16x32_bf16 v[6:9], v[194:197], v[238:241], v[6:9]
	v_mfma_f32_16x16x32_bf16 v[2:5], v[202:205], v[238:241], v[2:5]
	v_mfma_f32_16x16x32_bf16 v[54:57], v[198:201], v[218:221], v[54:57]
	v_mfma_f32_16x16x32_bf16 v[50:53], v[206:209], v[218:221], v[50:53]
	v_mfma_f32_16x16x32_bf16 v[38:41], v[198:201], v[226:229], v[38:41]
	v_mfma_f32_16x16x32_bf16 v[34:37], v[206:209], v[226:229], v[34:37]
	v_mfma_f32_16x16x32_bf16 v[22:25], v[198:201], v[234:237], v[22:25]
	v_mfma_f32_16x16x32_bf16 v[18:21], v[206:209], v[234:237], v[18:21]
	v_mfma_f32_16x16x32_bf16 v[6:9], v[198:201], v[242:245], v[6:9]
	v_mfma_f32_16x16x32_bf16 v[2:5], v[206:209], v[242:245], v[2:5]
	s_setprio 0
	s_barrier
	s_add_i32 s78, s78, 2
	s_add_u32 s60, s60, 0x100
	s_addc_u32 s61, s61, 0
	s_cmp_gt_u32 s78, 29
	s_cbranch_scc1 .LBB0_80

; #define LAS __attribute__((address_space(3)))
; __device__ __forceinline__ float allred16(float x) { x += dpp_f<0xB1>(x); x += dpp_f<0x4E>(x); x += dpp_f<0x141>(x); x += dpp_f<0x140>(x); return x; }
; __device__ __forceinline__ void phase_scan(const Args& a, int l, LAS unsigned char* lds) {
;     ...
;             for (int it = -6; it < NCH; ++it) {
;                 if (it >= 0) {
;                     const LAS float* tb = buf + (it % NB) * TC * TOKF;
;                     LAS float* yb = ybuf + (it & 1) * TC * 16;
;                     f32x4 w = *(const LAS f32x4*)(tb + 4 * j), kk = *(const LAS f32x4*)(tb + 64 + 4 * j), bv = *(const LAS f32x4*)(tb + 128 + 4 * j);
;                     f32x4 kv = *(const LAS f32x4*)(tb + 192 + 4 * j), wr = *(const LAS f32x4*)(tb + 256 + 4 * j);
;                     float vv = tb[320 + rowl];
;                     float yv = 0.f;
; #pragma unroll
;                     for (int t = 0; t < TC; ++t) {
;                         f32x4 nw = w, nkk = kk, nbv = bv, nkv = kv, nwr = wr; float nvv = vv;
;                         if (t + 1 < TC) { const LAS float* p = tb + (t + 1) * TOKF;
;                             nw = *(const LAS f32x4*)(p + 4 * j); nkk = *(const LAS f32x4*)(p + 64 + 4 * j); nbv = *(const LAS f32x4*)(p + 128 + 4 * j);
;                             nkv = *(const LAS f32x4*)(p + 192 + 4 * j); nwr = *(const LAS f32x4*)(p + 256 + 4 * j); nvv = p[320 + rowl]; }
;                         f32x2 ta = Sl * kk.lo; ta = Sh * kk.hi + ta;
;                         float pa = ta.x + ta.y;
;                         const f32x2 tl = Sl * w.lo + kv.lo * vv, th = Sh * w.hi + kv.hi * vv;
;                         pa = allred16(pa);
;                         Sl = bv.lo * pa + tl;
;                         Sh = bv.hi * pa + th;
;                         f32x2 ty = Sl * wr.lo; ty = Sh * wr.hi + ty;
;                         float y = ty.x + ty.y;
;                         y = allred16(y);
;                         yv = (j == t) ? y : yv;
;                         w = nw; kk = nkk; bv = nbv; kv = nkv; wr = nwr; vv = nvv;
;                     }
.LBB0_167:
	s_add_i32 s0, s0, 1
	s_addk_i32 s1, 0x100
	s_and_b32 s38, s0, 0xff
	s_mulk_i32 s38, 0xcd
	s_lshr_b32 s38, s38, 10
	s_mul_i32 s38, s38, 5
	s_sub_i32 s38, s0, s38
	s_and_b32 s38, s38, 0xff
	s_mulk_i32 s38, 0x5500
	v_lshl_add_u32 v50, v192, 2, s38
	v_lshl_add_u32 v51, v103, 2, s38
	s_and_b32 s38, s1, 0x100
	s_waitcnt lgkmcnt(0)
	s_barrier
	s_cmpk_eq_i32 s0, 0x100
	s_cbranch_scc1 .LBB0_170
.LBB0_168:
	s_cmp_lt_i32 s0, 0
	s_cbranch_scc1 .LBB0_167
	ds_read_b128 v[10:13], v50 offset:256
	ds_read_b128 v[6:9], v50 offset:0
	ds_read_b128 v[18:21], v50 offset:768
	ds_read_b32 v26, v51 offset:1280
	ds_read_b128 v[14:17], v50 offset:512
	ds_read_b128 v[22:25], v50 offset:1024
	ds_read_b128 v[32:35], v50 offset:1616
	ds_read_b128 v[28:31], v50 offset:1360
	ds_read_b128 v[40:43], v50 offset:2128
	ds_read_b32 v48, v51 offset:2640
	ds_read_b128 v[36:39], v50 offset:1872
	ds_read_b128 v[44:47], v50 offset:2384
	s_waitcnt lgkmcnt(6)
	v_pk_mul_f32 v[76:77], v[2:3], v[10:11]
	ds_read_b128 v[58:61], v50 offset:2976
	v_pk_fma_f32 v[76:77], v[4:5], v[12:13], v[76:77]
	v_pk_mul_f32 v[80:81], v[18:19], v[26:27] op_sel_hi:[1,0]
	v_add_f32_e32 v78, v76, v77
	v_pk_mul_f32 v[82:83], v[20:21], v[26:27] op_sel_hi:[1,0]
	s_nop 0
	v_add_f32_dpp v78, v78, v78 quad_perm:[1,0,3,2] row_mask:0xf bank_mask:0xf bound_ctrl:1
	v_pk_fma_f32 v[80:81], v[2:3], v[6:7], v[80:81]
	s_nop 0
	v_add_f32_dpp v78, v78, v78 quad_perm:[2,3,0,1] row_mask:0xf bank_mask:0xf bound_ctrl:1
	v_pk_fma_f32 v[82:83], v[4:5], v[8:9], v[82:83]
	s_nop 0
	v_add_f32_dpp v78, v78, v78 row_half_mirror row_mask:0xf bank_mask:0xf bound_ctrl:1
	ds_read_b128 v[54:57], v50 offset:2720
	ds_read_b128 v[66:69], v50 offset:3488
	v_add_f32_dpp v78, v78, v78 row_mirror row_mask:0xf bank_mask:0xf bound_ctrl:1
	v_pk_fma_f32 v[2:3], v[14:15], v[78:79], v[80:81] op_sel_hi:[1,0,1]
	v_pk_fma_f32 v[4:5], v[16:17], v[78:79], v[82:83] op_sel_hi:[1,0,1]
	ds_read_b32 v74, v51 offset:4000
	ds_read_b128 v[62:65], v50 offset:3232
	ds_read_b128 v[70:73], v50 offset:3744
	s_waitcnt lgkmcnt(6)
	v_pk_mul_f32 v[76:77], v[2:3], v[32:33]
	ds_read_b128 v[108:111], v50 offset:4336
	v_pk_fma_f32 v[76:77], v[4:5], v[34:35], v[76:77]
	v_pk_mul_f32 v[80:81], v[40:41], v[48:49] op_sel_hi:[1,0]
	v_add_f32_e32 v78, v76, v77
	v_pk_mul_f32 v[82:83], v[42:43], v[48:49] op_sel_hi:[1,0]
	v_pk_mul_f32 v[84:85], v[22:23], v[2:3]
	v_add_f32_dpp v78, v78, v78 quad_perm:[1,0,3,2] row_mask:0xf bank_mask:0xf bound_ctrl:1
	v_pk_fma_f32 v[84:85], v[24:25], v[4:5], v[84:85]
	v_pk_fma_f32 v[80:81], v[2:3], v[28:29], v[80:81]
	v_add_f32_dpp v78, v78, v78 quad_perm:[2,3,0,1] row_mask:0xf bank_mask:0xf bound_ctrl:1
	v_add_f32_e32 v86, v84, v85
	v_pk_fma_f32 v[82:83], v[4:5], v[30:31], v[82:83]
	v_add_f32_dpp v78, v78, v78 row_half_mirror row_mask:0xf bank_mask:0xf bound_ctrl:1
	ds_read_b128 v[104:107], v50 offset:4080
	ds_read_b128 v[116:119], v50 offset:4848
	v_add_f32_dpp v78, v78, v78 row_mirror row_mask:0xf bank_mask:0xf bound_ctrl:1
	v_pk_fma_f32 v[2:3], v[36:37], v[78:79], v[80:81] op_sel_hi:[1,0,1]
	v_pk_fma_f32 v[4:5], v[38:39], v[78:79], v[82:83] op_sel_hi:[1,0,1]
	ds_read_b32 v124, v51 offset:5360
	ds_read_b128 v[112:115], v50 offset:4592
	ds_read_b128 v[120:123], v50 offset:5104
	s_waitcnt lgkmcnt(6)
	v_pk_mul_f32 v[76:77], v[2:3], v[58:59]
	ds_read_b128 v[10:13], v50 offset:5696
	v_pk_fma_f32 v[76:77], v[4:5], v[60:61], v[76:77]
	v_pk_mul_f32 v[80:81], v[66:67], v[74:75] op_sel_hi:[1,0]
	v_add_f32_e32 v78, v76, v77
	v_pk_mul_f32 v[82:83], v[68:69], v[74:75] op_sel_hi:[1,0]
	v_pk_mul_f32 v[84:85], v[44:45], v[2:3]
	v_add_f32_dpp v78, v78, v78 quad_perm:[1,0,3,2] row_mask:0xf bank_mask:0xf bound_ctrl:1
	v_pk_fma_f32 v[84:85], v[46:47], v[4:5], v[84:85]
	v_pk_fma_f32 v[80:81], v[2:3], v[54:55], v[80:81]
	v_add_f32_dpp v78, v78, v78 quad_perm:[2,3,0,1] row_mask:0xf bank_mask:0xf bound_ctrl:1
	v_add_f32_e32 v87, v84, v85
	v_pk_fma_f32 v[82:83], v[4:5], v[56:57], v[82:83]
	v_add_f32_dpp v78, v78, v78 row_half_mirror row_mask:0xf bank_mask:0xf bound_ctrl:1
	ds_read_b128 v[6:9], v50 offset:5440
	ds_read_b128 v[18:21], v50 offset:6208
	v_add_f32_dpp v78, v78, v78 row_mirror row_mask:0xf bank_mask:0xf bound_ctrl:1
	v_pk_fma_f32 v[2:3], v[62:63], v[78:79], v[80:81] op_sel_hi:[1,0,1]
	v_pk_fma_f32 v[4:5], v[64:65], v[78:79], v[82:83] op_sel_hi:[1,0,1]
	ds_read_b32 v26, v51 offset:6720
	ds_read_b128 v[14:17], v50 offset:5952
	ds_read_b128 v[22:25], v50 offset:6464
	s_waitcnt lgkmcnt(6)
	v_pk_mul_f32 v[76:77], v[2:3], v[108:109]
	ds_read_b128 v[32:35], v50 offset:7056
	v_pk_fma_f32 v[76:77], v[4:5], v[110:111], v[76:77]
	v_pk_mul_f32 v[80:81], v[116:117], v[124:125] op_sel_hi:[1,0]
	v_add_f32_e32 v78, v76, v77
	v_pk_mul_f32 v[82:83], v[118:119], v[124:125] op_sel_hi:[1,0]
	v_pk_mul_f32 v[84:85], v[70:71], v[2:3]
	v_add_f32_dpp v78, v78, v78 quad_perm:[1,0,3,2] row_mask:0xf bank_mask:0xf bound_ctrl:1
	v_pk_fma_f32 v[84:85], v[72:73], v[4:5], v[84:85]
	v_pk_fma_f32 v[80:81], v[2:3], v[104:105], v[80:81]
	v_add_f32_dpp v78, v78, v78 quad_perm:[2,3,0,1] row_mask:0xf bank_mask:0xf bound_ctrl:1
	v_add_f32_e32 v88, v84, v85
	v_pk_fma_f32 v[82:83], v[4:5], v[106:107], v[82:83]
	v_add_f32_dpp v78, v78, v78 row_half_mirror row_mask:0xf bank_mask:0xf bound_ctrl:1
	ds_read_b128 v[28:31], v50 offset:6800
	ds_read_b128 v[40:43], v50 offset:7568
	v_add_f32_dpp v78, v78, v78 row_mirror row_mask:0xf bank_mask:0xf bound_ctrl:1
	v_pk_fma_f32 v[2:3], v[112:113], v[78:79], v[80:81] op_sel_hi:[1,0,1]
	v_pk_fma_f32 v[4:5], v[114:115], v[78:79], v[82:83] op_sel_hi:[1,0,1]
	ds_read_b32 v48, v51 offset:8080
	ds_read_b128 v[36:39], v50 offset:7312
	ds_read_b128 v[44:47], v50 offset:7824
	s_waitcnt lgkmcnt(6)
; #define LAS __attribute__((address_space(3)))
; __device__ __forceinline__ float allred16(float x) { x += dpp_f<0xB1>(x); x += dpp_f<0x4E>(x); x += dpp_f<0x141>(x); x += dpp_f<0x140>(x); return x; }
; __device__ __forceinline__ void phase_scan(const Args& a, int l, LAS unsigned char* lds) {
;     ...
;                     for (int t = 0; t < TC; ++t) {
;                         f32x4 nw = w, nkk = kk, nbv = bv, nkv = kv, nwr = wr; float nvv = vv;
;                         if (t + 1 < TC) { const LAS float* p = tb + (t + 1) * TOKF;
;                             nw = *(const LAS f32x4*)(p + 4 * j); nkk = *(const LAS f32x4*)(p + 64 + 4 * j); nbv = *(const LAS f32x4*)(p + 128 + 4 * j);
;                             nkv = *(const LAS f32x4*)(p + 192 + 4 * j); nwr = *(const LAS f32x4*)(p + 256 + 4 * j); nvv = p[320 + rowl]; }
;                         f32x2 ta = Sl * kk.lo; ta = Sh * kk.hi + ta;
;                         float pa = ta.x + ta.y;
;                         const f32x2 tl = Sl * w.lo + kv.lo * vv, th = Sh * w.hi + kv.hi * vv;
;                         pa = allred16(pa);
;                         Sl = bv.lo * pa + tl;
;                         Sh = bv.hi * pa + th;
;                         f32x2 ty = Sl * wr.lo; ty = Sh * wr.hi + ty;
;                         float y = ty.x + ty.y;
;                         y = allred16(y);
;                         yv = (j == t) ? y : yv;
;                         w = nw; kk = nkk; bv = nbv; kv = nkv; wr = nwr; vv = nvv;
	v_pk_mul_f32 v[76:77], v[2:3], v[10:11]
	ds_read_b128 v[58:61], v50 offset:8416
	v_pk_fma_f32 v[76:77], v[4:5], v[12:13], v[76:77]
	v_pk_mul_f32 v[80:81], v[18:19], v[26:27] op_sel_hi:[1,0]
	v_add_f32_e32 v78, v76, v77
	v_pk_mul_f32 v[82:83], v[20:21], v[26:27] op_sel_hi:[1,0]
	v_pk_mul_f32 v[84:85], v[120:121], v[2:3]
	v_add_f32_dpp v78, v78, v78 quad_perm:[1,0,3,2] row_mask:0xf bank_mask:0xf bound_ctrl:1
	v_pk_fma_f32 v[84:85], v[122:123], v[4:5], v[84:85]
	v_pk_fma_f32 v[80:81], v[2:3], v[6:7], v[80:81]
	v_add_f32_dpp v78, v78, v78 quad_perm:[2,3,0,1] row_mask:0xf bank_mask:0xf bound_ctrl:1
	v_add_f32_e32 v89, v84, v85
	v_pk_fma_f32 v[82:83], v[4:5], v[8:9], v[82:83]
	v_add_f32_dpp v78, v78, v78 row_half_mirror row_mask:0xf bank_mask:0xf bound_ctrl:1
	ds_read_b128 v[54:57], v50 offset:8160
	ds_read_b128 v[66:69], v50 offset:8928
	v_add_f32_dpp v78, v78, v78 row_mirror row_mask:0xf bank_mask:0xf bound_ctrl:1
	v_pk_fma_f32 v[2:3], v[14:15], v[78:79], v[80:81] op_sel_hi:[1,0,1]
	v_pk_fma_f32 v[4:5], v[16:17], v[78:79], v[82:83] op_sel_hi:[1,0,1]
	ds_read_b32 v74, v51 offset:9440
	ds_read_b128 v[62:65], v50 offset:8672
	ds_read_b128 v[70:73], v50 offset:9184
	s_waitcnt lgkmcnt(6)
	v_pk_mul_f32 v[76:77], v[2:3], v[32:33]
	ds_read_b128 v[108:111], v50 offset:9776
	v_pk_fma_f32 v[76:77], v[4:5], v[34:35], v[76:77]
	v_pk_mul_f32 v[80:81], v[40:41], v[48:49] op_sel_hi:[1,0]
	v_add_f32_e32 v78, v76, v77
	v_pk_mul_f32 v[82:83], v[42:43], v[48:49] op_sel_hi:[1,0]
	v_pk_mul_f32 v[84:85], v[22:23], v[2:3]
	v_add_f32_dpp v78, v78, v78 quad_perm:[1,0,3,2] row_mask:0xf bank_mask:0xf bound_ctrl:1
	v_pk_fma_f32 v[84:85], v[24:25], v[4:5], v[84:85]
	v_pk_fma_f32 v[80:81], v[2:3], v[28:29], v[80:81]
	v_add_f32_dpp v78, v78, v78 quad_perm:[2,3,0,1] row_mask:0xf bank_mask:0xf bound_ctrl:1
	v_add_f32_e32 v90, v84, v85
	v_pk_fma_f32 v[82:83], v[4:5], v[30:31], v[82:83]
	v_add_f32_dpp v78, v78, v78 row_half_mirror row_mask:0xf bank_mask:0xf bound_ctrl:1
	ds_read_b128 v[104:107], v50 offset:9520
	ds_read_b128 v[116:119], v50 offset:10288
	v_add_f32_dpp v78, v78, v78 row_mirror row_mask:0xf bank_mask:0xf bound_ctrl:1
	v_pk_fma_f32 v[2:3], v[36:37], v[78:79], v[80:81] op_sel_hi:[1,0,1]
	v_pk_fma_f32 v[4:5], v[38:39], v[78:79], v[82:83] op_sel_hi:[1,0,1]
	ds_read_b32 v124, v51 offset:10800
	ds_read_b128 v[112:115], v50 offset:10032
	ds_read_b128 v[120:123], v50 offset:10544
	s_waitcnt lgkmcnt(6)
	v_pk_mul_f32 v[76:77], v[2:3], v[58:59]
	ds_read_b128 v[10:13], v50 offset:11136
	v_pk_fma_f32 v[76:77], v[4:5], v[60:61], v[76:77]
	v_pk_mul_f32 v[80:81], v[66:67], v[74:75] op_sel_hi:[1,0]
	v_add_f32_e32 v78, v76, v77
	v_pk_mul_f32 v[82:83], v[68:69], v[74:75] op_sel_hi:[1,0]
	v_pk_mul_f32 v[84:85], v[44:45], v[2:3]
	v_add_f32_dpp v78, v78, v78 quad_perm:[1,0,3,2] row_mask:0xf bank_mask:0xf bound_ctrl:1
	v_pk_fma_f32 v[84:85], v[46:47], v[4:5], v[84:85]
	v_pk_fma_f32 v[80:81], v[2:3], v[54:55], v[80:81]
	v_add_f32_dpp v78, v78, v78 quad_perm:[2,3,0,1] row_mask:0xf bank_mask:0xf bound_ctrl:1
	v_add_f32_e32 v91, v84, v85
	v_pk_fma_f32 v[82:83], v[4:5], v[56:57], v[82:83]
	v_add_f32_dpp v78, v78, v78 row_half_mirror row_mask:0xf bank_mask:0xf bound_ctrl:1
	ds_read_b128 v[6:9], v50 offset:10880
	ds_read_b128 v[18:21], v50 offset:11648
	v_add_f32_dpp v78, v78, v78 row_mirror row_mask:0xf bank_mask:0xf bound_ctrl:1
	v_pk_fma_f32 v[2:3], v[62:63], v[78:79], v[80:81] op_sel_hi:[1,0,1]
	v_pk_fma_f32 v[4:5], v[64:65], v[78:79], v[82:83] op_sel_hi:[1,0,1]
	ds_read_b32 v26, v51 offset:12160
	ds_read_b128 v[14:17], v50 offset:11392
	ds_read_b128 v[22:25], v50 offset:11904
	s_waitcnt lgkmcnt(6)
	v_pk_mul_f32 v[76:77], v[2:3], v[108:109]
	ds_read_b128 v[32:35], v50 offset:12496
	v_pk_fma_f32 v[76:77], v[4:5], v[110:111], v[76:77]
	v_pk_mul_f32 v[80:81], v[116:117], v[124:125] op_sel_hi:[1,0]
	v_add_f32_e32 v78, v76, v77
	v_pk_mul_f32 v[82:83], v[118:119], v[124:125] op_sel_hi:[1,0]
	v_pk_mul_f32 v[84:85], v[70:71], v[2:3]
	v_add_f32_dpp v78, v78, v78 quad_perm:[1,0,3,2] row_mask:0xf bank_mask:0xf bound_ctrl:1
	v_pk_fma_f32 v[84:85], v[72:73], v[4:5], v[84:85]
	v_pk_fma_f32 v[80:81], v[2:3], v[104:105], v[80:81]
	v_add_f32_dpp v78, v78, v78 quad_perm:[2,3,0,1] row_mask:0xf bank_mask:0xf bound_ctrl:1
	v_add_f32_e32 v92, v84, v85
	v_pk_fma_f32 v[82:83], v[4:5], v[106:107], v[82:83]
	v_add_f32_dpp v78, v78, v78 row_half_mirror row_mask:0xf bank_mask:0xf bound_ctrl:1
	ds_read_b128 v[28:31], v50 offset:12240
	ds_read_b128 v[40:43], v50 offset:13008
	v_add_f32_dpp v78, v78, v78 row_mirror row_mask:0xf bank_mask:0xf bound_ctrl:1
	v_pk_fma_f32 v[2:3], v[112:113], v[78:79], v[80:81] op_sel_hi:[1,0,1]
	v_pk_fma_f32 v[4:5], v[114:115], v[78:79], v[82:83] op_sel_hi:[1,0,1]
	ds_read_b32 v48, v51 offset:13520
	ds_read_b128 v[36:39], v50 offset:12752
	ds_read_b128 v[44:47], v50 offset:13264
	s_waitcnt lgkmcnt(6)
	v_pk_mul_f32 v[76:77], v[2:3], v[10:11]
	ds_read_b128 v[58:61], v50 offset:13856
	v_pk_fma_f32 v[76:77], v[4:5], v[12:13], v[76:77]
	v_pk_mul_f32 v[80:81], v[18:19], v[26:27] op_sel_hi:[1,0]
	v_add_f32_e32 v78, v76, v77
	v_pk_mul_f32 v[82:83], v[20:21], v[26:27] op_sel_hi:[1,0]
	v_pk_mul_f32 v[84:85], v[120:121], v[2:3]
	v_add_f32_dpp v78, v78, v78 quad_perm:[1,0,3,2] row_mask:0xf bank_mask:0xf bound_ctrl:1
	v_pk_fma_f32 v[84:85], v[122:123], v[4:5], v[84:85]
	v_pk_fma_f32 v[80:81], v[2:3], v[6:7], v[80:81]
	v_add_f32_dpp v78, v78, v78 quad_perm:[2,3,0,1] row_mask:0xf bank_mask:0xf bound_ctrl:1
	v_add_f32_e32 v93, v84, v85
	v_pk_fma_f32 v[82:83], v[4:5], v[8:9], v[82:83]
	v_add_f32_dpp v78, v78, v78 row_half_mirror row_mask:0xf bank_mask:0xf bound_ctrl:1
	ds_read_b128 v[54:57], v50 offset:13600
	ds_read_b128 v[66:69], v50 offset:14368
	v_add_f32_dpp v78, v78, v78 row_mirror row_mask:0xf bank_mask:0xf bound_ctrl:1
	v_pk_fma_f32 v[2:3], v[14:15], v[78:79], v[80:81] op_sel_hi:[1,0,1]
	v_pk_fma_f32 v[4:5], v[16:17], v[78:79], v[82:83] op_sel_hi:[1,0,1]
	ds_read_b32 v74, v51 offset:14880
	ds_read_b128 v[62:65], v50 offset:14112
	ds_read_b128 v[70:73], v50 offset:14624
	s_waitcnt lgkmcnt(6)
; #define LAS __attribute__((address_space(3)))
; __device__ __forceinline__ float allred16(float x) { x += dpp_f<0xB1>(x); x += dpp_f<0x4E>(x); x += dpp_f<0x141>(x); x += dpp_f<0x140>(x); return x; }
; __device__ __forceinline__ void phase_scan(const Args& a, int l, LAS unsigned char* lds) {
;     ...
;                     for (int t = 0; t < TC; ++t) {
;                         f32x4 nw = w, nkk = kk, nbv = bv, nkv = kv, nwr = wr; float nvv = vv;
;                         if (t + 1 < TC) { const LAS float* p = tb + (t + 1) * TOKF;
;                             nw = *(const LAS f32x4*)(p + 4 * j); nkk = *(const LAS f32x4*)(p + 64 + 4 * j); nbv = *(const LAS f32x4*)(p + 128 + 4 * j);
;                             nkv = *(const LAS f32x4*)(p + 192 + 4 * j); nwr = *(const LAS f32x4*)(p + 256 + 4 * j); nvv = p[320 + rowl]; }
;                         f32x2 ta = Sl * kk.lo; ta = Sh * kk.hi + ta;
;                         float pa = ta.x + ta.y;
;                         const f32x2 tl = Sl * w.lo + kv.lo * vv, th = Sh * w.hi + kv.hi * vv;
;                         pa = allred16(pa);
;                         Sl = bv.lo * pa + tl;
;                         Sh = bv.hi * pa + th;
;                         f32x2 ty = Sl * wr.lo; ty = Sh * wr.hi + ty;
;                         float y = ty.x + ty.y;
;                         y = allred16(y);
;                         yv = (j == t) ? y : yv;
;                         w = nw; kk = nkk; bv = nbv; kv = nkv; wr = nwr; vv = nvv;
	v_pk_mul_f32 v[76:77], v[2:3], v[32:33]
	ds_read_b128 v[108:111], v50 offset:15216
	v_pk_fma_f32 v[76:77], v[4:5], v[34:35], v[76:77]
	v_pk_mul_f32 v[80:81], v[40:41], v[48:49] op_sel_hi:[1,0]
	v_add_f32_e32 v78, v76, v77
	v_pk_mul_f32 v[82:83], v[42:43], v[48:49] op_sel_hi:[1,0]
	v_pk_mul_f32 v[84:85], v[22:23], v[2:3]
	v_add_f32_dpp v78, v78, v78 quad_perm:[1,0,3,2] row_mask:0xf bank_mask:0xf bound_ctrl:1
	v_pk_fma_f32 v[84:85], v[24:25], v[4:5], v[84:85]
	v_pk_fma_f32 v[80:81], v[2:3], v[28:29], v[80:81]
	v_add_f32_dpp v78, v78, v78 quad_perm:[2,3,0,1] row_mask:0xf bank_mask:0xf bound_ctrl:1
	v_add_f32_e32 v94, v84, v85
	v_pk_fma_f32 v[82:83], v[4:5], v[30:31], v[82:83]
	v_add_f32_dpp v78, v78, v78 row_half_mirror row_mask:0xf bank_mask:0xf bound_ctrl:1
	ds_read_b128 v[104:107], v50 offset:14960
	ds_read_b128 v[116:119], v50 offset:15728
	v_add_f32_dpp v78, v78, v78 row_mirror row_mask:0xf bank_mask:0xf bound_ctrl:1
	v_pk_fma_f32 v[2:3], v[36:37], v[78:79], v[80:81] op_sel_hi:[1,0,1]
	v_pk_fma_f32 v[4:5], v[38:39], v[78:79], v[82:83] op_sel_hi:[1,0,1]
	ds_read_b32 v124, v51 offset:16240
	ds_read_b128 v[112:115], v50 offset:15472
	ds_read_b128 v[120:123], v50 offset:15984
	s_waitcnt lgkmcnt(6)
	v_pk_mul_f32 v[76:77], v[2:3], v[58:59]
	ds_read_b128 v[10:13], v50 offset:16576
	v_pk_fma_f32 v[76:77], v[4:5], v[60:61], v[76:77]
	v_pk_mul_f32 v[80:81], v[66:67], v[74:75] op_sel_hi:[1,0]
	v_add_f32_e32 v78, v76, v77
	v_pk_mul_f32 v[82:83], v[68:69], v[74:75] op_sel_hi:[1,0]
	v_pk_mul_f32 v[84:85], v[44:45], v[2:3]
	v_add_f32_dpp v78, v78, v78 quad_perm:[1,0,3,2] row_mask:0xf bank_mask:0xf bound_ctrl:1
	v_pk_fma_f32 v[84:85], v[46:47], v[4:5], v[84:85]
	v_pk_fma_f32 v[80:81], v[2:3], v[54:55], v[80:81]
	v_add_f32_dpp v78, v78, v78 quad_perm:[2,3,0,1] row_mask:0xf bank_mask:0xf bound_ctrl:1
	v_add_f32_e32 v95, v84, v85
	v_pk_fma_f32 v[82:83], v[4:5], v[56:57], v[82:83]
	v_add_f32_dpp v78, v78, v78 row_half_mirror row_mask:0xf bank_mask:0xf bound_ctrl:1
	ds_read_b128 v[6:9], v50 offset:16320
	ds_read_b128 v[18:21], v50 offset:17088
	v_add_f32_dpp v78, v78, v78 row_mirror row_mask:0xf bank_mask:0xf bound_ctrl:1
	v_pk_fma_f32 v[2:3], v[62:63], v[78:79], v[80:81] op_sel_hi:[1,0,1]
	v_pk_fma_f32 v[4:5], v[64:65], v[78:79], v[82:83] op_sel_hi:[1,0,1]
	ds_read_b32 v26, v51 offset:17600
	ds_read_b128 v[14:17], v50 offset:16832
	ds_read_b128 v[22:25], v50 offset:17344
	s_waitcnt lgkmcnt(6)
	v_pk_mul_f32 v[76:77], v[2:3], v[108:109]
	ds_read_b128 v[32:35], v50 offset:17936
	v_pk_fma_f32 v[76:77], v[4:5], v[110:111], v[76:77]
	v_pk_mul_f32 v[80:81], v[116:117], v[124:125] op_sel_hi:[1,0]
	v_add_f32_e32 v78, v76, v77
	v_pk_mul_f32 v[82:83], v[118:119], v[124:125] op_sel_hi:[1,0]
	v_pk_mul_f32 v[84:85], v[70:71], v[2:3]
	v_add_f32_dpp v78, v78, v78 quad_perm:[1,0,3,2] row_mask:0xf bank_mask:0xf bound_ctrl:1
	v_pk_fma_f32 v[84:85], v[72:73], v[4:5], v[84:85]
	v_pk_fma_f32 v[80:81], v[2:3], v[104:105], v[80:81]
	v_add_f32_dpp v78, v78, v78 quad_perm:[2,3,0,1] row_mask:0xf bank_mask:0xf bound_ctrl:1
	v_add_f32_e32 v126, v84, v85
	v_pk_fma_f32 v[82:83], v[4:5], v[106:107], v[82:83]
	v_add_f32_dpp v78, v78, v78 row_half_mirror row_mask:0xf bank_mask:0xf bound_ctrl:1
	ds_read_b128 v[28:31], v50 offset:17680
	ds_read_b128 v[40:43], v50 offset:18448
	v_add_f32_dpp v78, v78, v78 row_mirror row_mask:0xf bank_mask:0xf bound_ctrl:1
	v_pk_fma_f32 v[2:3], v[112:113], v[78:79], v[80:81] op_sel_hi:[1,0,1]
	v_pk_fma_f32 v[4:5], v[114:115], v[78:79], v[82:83] op_sel_hi:[1,0,1]
	ds_read_b32 v48, v51 offset:18960
	ds_read_b128 v[36:39], v50 offset:18192
	ds_read_b128 v[44:47], v50 offset:18704
	s_waitcnt lgkmcnt(6)
	v_pk_mul_f32 v[76:77], v[2:3], v[10:11]
	ds_read_b128 v[58:61], v50 offset:19296
	v_pk_fma_f32 v[76:77], v[4:5], v[12:13], v[76:77]
	v_pk_mul_f32 v[80:81], v[18:19], v[26:27] op_sel_hi:[1,0]
	v_add_f32_e32 v78, v76, v77
	v_pk_mul_f32 v[82:83], v[20:21], v[26:27] op_sel_hi:[1,0]
	v_pk_mul_f32 v[84:85], v[120:121], v[2:3]
	v_add_f32_dpp v78, v78, v78 quad_perm:[1,0,3,2] row_mask:0xf bank_mask:0xf bound_ctrl:1
	v_pk_fma_f32 v[84:85], v[122:123], v[4:5], v[84:85]
	v_pk_fma_f32 v[80:81], v[2:3], v[6:7], v[80:81]
	v_add_f32_dpp v78, v78, v78 quad_perm:[2,3,0,1] row_mask:0xf bank_mask:0xf bound_ctrl:1
	v_add_f32_e32 v127, v84, v85
	v_pk_fma_f32 v[82:83], v[4:5], v[8:9], v[82:83]
	v_add_f32_dpp v78, v78, v78 row_half_mirror row_mask:0xf bank_mask:0xf bound_ctrl:1
	ds_read_b128 v[54:57], v50 offset:19040
	ds_read_b128 v[66:69], v50 offset:19808
	v_add_f32_dpp v78, v78, v78 row_mirror row_mask:0xf bank_mask:0xf bound_ctrl:1
	v_pk_fma_f32 v[2:3], v[14:15], v[78:79], v[80:81] op_sel_hi:[1,0,1]
	v_pk_fma_f32 v[4:5], v[16:17], v[78:79], v[82:83] op_sel_hi:[1,0,1]
	ds_read_b32 v74, v51 offset:20320
	ds_read_b128 v[62:65], v50 offset:19552
	ds_read_b128 v[70:73], v50 offset:20064
	s_waitcnt lgkmcnt(6)
; #define LAS __attribute__((address_space(3)))
; __device__ __forceinline__ float allred16(float x) { x += dpp_f<0xB1>(x); x += dpp_f<0x4E>(x); x += dpp_f<0x141>(x); x += dpp_f<0x140>(x); return x; }
; __device__ __forceinline__ void phase_scan(const Args& a, int l, LAS unsigned char* lds) {
;     ...
;                     for (int t = 0; t < TC; ++t) {
;                         f32x4 nw = w, nkk = kk, nbv = bv, nkv = kv, nwr = wr; float nvv = vv;
;                         if (t + 1 < TC) { const LAS float* p = tb + (t + 1) * TOKF;
;                             nw = *(const LAS f32x4*)(p + 4 * j); nkk = *(const LAS f32x4*)(p + 64 + 4 * j); nbv = *(const LAS f32x4*)(p + 128 + 4 * j);
;                             nkv = *(const LAS f32x4*)(p + 192 + 4 * j); nwr = *(const LAS f32x4*)(p + 256 + 4 * j); nvv = p[320 + rowl]; }
;                         f32x2 ta = Sl * kk.lo; ta = Sh * kk.hi + ta;
;                         float pa = ta.x + ta.y;
;                         const f32x2 tl = Sl * w.lo + kv.lo * vv, th = Sh * w.hi + kv.hi * vv;
;                         pa = allred16(pa);
;                         Sl = bv.lo * pa + tl;
;                         Sh = bv.hi * pa + th;
;                         f32x2 ty = Sl * wr.lo; ty = Sh * wr.hi + ty;
;                         float y = ty.x + ty.y;
;                         y = allred16(y);
;                         yv = (j == t) ? y : yv;
;                         w = nw; kk = nkk; bv = nbv; kv = nkv; wr = nwr; vv = nvv;
;                     }
;                     yb[j * 16 + rowl] = yv;
	v_pk_mul_f32 v[76:77], v[2:3], v[32:33]
	ds_read_b128 v[108:111], v50 offset:20656
	v_pk_fma_f32 v[76:77], v[4:5], v[34:35], v[76:77]
	v_pk_mul_f32 v[80:81], v[40:41], v[48:49] op_sel_hi:[1,0]
	v_add_f32_e32 v78, v76, v77
	v_pk_mul_f32 v[82:83], v[42:43], v[48:49] op_sel_hi:[1,0]
	v_pk_mul_f32 v[84:85], v[22:23], v[2:3]
	v_add_f32_dpp v78, v78, v78 quad_perm:[1,0,3,2] row_mask:0xf bank_mask:0xf bound_ctrl:1
	v_pk_fma_f32 v[84:85], v[24:25], v[4:5], v[84:85]
	v_pk_fma_f32 v[80:81], v[2:3], v[28:29], v[80:81]
	v_add_f32_dpp v78, v78, v78 quad_perm:[2,3,0,1] row_mask:0xf bank_mask:0xf bound_ctrl:1
	v_add_f32_e32 v128, v84, v85
	v_pk_fma_f32 v[82:83], v[4:5], v[30:31], v[82:83]
	v_add_f32_dpp v78, v78, v78 row_half_mirror row_mask:0xf bank_mask:0xf bound_ctrl:1
	ds_read_b128 v[104:107], v50 offset:20400
	ds_read_b128 v[116:119], v50 offset:21168
	v_add_f32_dpp v78, v78, v78 row_mirror row_mask:0xf bank_mask:0xf bound_ctrl:1
	v_pk_fma_f32 v[2:3], v[36:37], v[78:79], v[80:81] op_sel_hi:[1,0,1]
	v_pk_fma_f32 v[4:5], v[38:39], v[78:79], v[82:83] op_sel_hi:[1,0,1]
	ds_read_b32 v124, v51 offset:21680
	ds_read_b128 v[112:115], v50 offset:20912
	ds_read_b128 v[120:123], v50 offset:21424
	s_waitcnt lgkmcnt(6)
	v_pk_mul_f32 v[76:77], v[2:3], v[58:59]
	s_nop 0
	v_pk_fma_f32 v[76:77], v[4:5], v[60:61], v[76:77]
	v_pk_mul_f32 v[80:81], v[66:67], v[74:75] op_sel_hi:[1,0]
	v_add_f32_e32 v78, v76, v77
	v_pk_mul_f32 v[82:83], v[68:69], v[74:75] op_sel_hi:[1,0]
	v_pk_mul_f32 v[84:85], v[44:45], v[2:3]
	v_add_f32_dpp v78, v78, v78 quad_perm:[1,0,3,2] row_mask:0xf bank_mask:0xf bound_ctrl:1
	v_pk_fma_f32 v[84:85], v[46:47], v[4:5], v[84:85]
	v_pk_fma_f32 v[80:81], v[2:3], v[54:55], v[80:81]
	v_add_f32_dpp v78, v78, v78 quad_perm:[2,3,0,1] row_mask:0xf bank_mask:0xf bound_ctrl:1
	v_add_f32_e32 v129, v84, v85
	v_pk_fma_f32 v[82:83], v[4:5], v[56:57], v[82:83]
	v_add_f32_dpp v78, v78, v78 row_half_mirror row_mask:0xf bank_mask:0xf bound_ctrl:1
	s_nop 1
	v_add_f32_dpp v78, v78, v78 row_mirror row_mask:0xf bank_mask:0xf bound_ctrl:1
	v_pk_fma_f32 v[2:3], v[62:63], v[78:79], v[80:81] op_sel_hi:[1,0,1]
	v_pk_fma_f32 v[4:5], v[64:65], v[78:79], v[82:83] op_sel_hi:[1,0,1]
	s_waitcnt lgkmcnt(0)
	v_pk_mul_f32 v[76:77], v[2:3], v[108:109]
	s_nop 0
	v_pk_fma_f32 v[76:77], v[4:5], v[110:111], v[76:77]
	v_pk_mul_f32 v[80:81], v[116:117], v[124:125] op_sel_hi:[1,0]
	v_add_f32_e32 v78, v76, v77
	v_pk_mul_f32 v[82:83], v[118:119], v[124:125] op_sel_hi:[1,0]
	v_pk_mul_f32 v[84:85], v[70:71], v[2:3]
	v_add_f32_dpp v78, v78, v78 quad_perm:[1,0,3,2] row_mask:0xf bank_mask:0xf bound_ctrl:1
	v_pk_fma_f32 v[84:85], v[72:73], v[4:5], v[84:85]
	v_pk_fma_f32 v[80:81], v[2:3], v[104:105], v[80:81]
	v_add_f32_dpp v78, v78, v78 quad_perm:[2,3,0,1] row_mask:0xf bank_mask:0xf bound_ctrl:1
	v_add_f32_e32 v130, v84, v85
	v_pk_fma_f32 v[82:83], v[4:5], v[106:107], v[82:83]
	v_add_f32_dpp v78, v78, v78 row_half_mirror row_mask:0xf bank_mask:0xf bound_ctrl:1
	s_nop 1
	v_add_f32_dpp v78, v78, v78 row_mirror row_mask:0xf bank_mask:0xf bound_ctrl:1
	v_pk_fma_f32 v[2:3], v[112:113], v[78:79], v[80:81] op_sel_hi:[1,0,1]
	v_pk_fma_f32 v[4:5], v[114:115], v[78:79], v[82:83] op_sel_hi:[1,0,1]
	v_pk_mul_f32 v[84:85], v[120:121], v[2:3]
	v_lshl_add_u32 v52, s38, 2, v193
	v_pk_fma_f32 v[84:85], v[122:123], v[4:5], v[84:85]
	s_nop 0
	v_add_f32_e32 v131, v84, v85
	v_add_f32_dpp v86, v86, v86 row_shl:8 row_mask:0xf bank_mask:0x3 bound_ctrl:1
	v_add_f32_dpp v86, v94, v94 row_shr:8 row_mask:0xf bank_mask:0xc bound_ctrl:1
	v_add_f32_dpp v87, v87, v87 row_shl:8 row_mask:0xf bank_mask:0x3 bound_ctrl:1
	v_add_f32_dpp v87, v95, v95 row_shr:8 row_mask:0xf bank_mask:0xc bound_ctrl:1
	v_add_f32_dpp v88, v88, v88 row_shl:8 row_mask:0xf bank_mask:0x3 bound_ctrl:1
	v_add_f32_dpp v88, v126, v126 row_shr:8 row_mask:0xf bank_mask:0xc bound_ctrl:1
	v_add_f32_dpp v89, v89, v89 row_shl:8 row_mask:0xf bank_mask:0x3 bound_ctrl:1
	v_add_f32_dpp v89, v127, v127 row_shr:8 row_mask:0xf bank_mask:0xc bound_ctrl:1
	v_add_f32_dpp v90, v90, v90 row_shl:8 row_mask:0xf bank_mask:0x3 bound_ctrl:1
	v_add_f32_dpp v90, v128, v128 row_shr:8 row_mask:0xf bank_mask:0xc bound_ctrl:1
	v_add_f32_dpp v91, v91, v91 row_shl:8 row_mask:0xf bank_mask:0x3 bound_ctrl:1
	v_add_f32_dpp v91, v129, v129 row_shr:8 row_mask:0xf bank_mask:0xc bound_ctrl:1
	v_add_f32_dpp v92, v92, v92 row_shl:8 row_mask:0xf bank_mask:0x3 bound_ctrl:1
	v_add_f32_dpp v92, v130, v130 row_shr:8 row_mask:0xf bank_mask:0xc bound_ctrl:1
	v_add_f32_dpp v93, v93, v93 row_shl:8 row_mask:0xf bank_mask:0x3 bound_ctrl:1
	v_add_f32_dpp v93, v131, v131 row_shr:8 row_mask:0xf bank_mask:0xc bound_ctrl:1
	v_cmp_ne_u32_e32 vcc, 0, v138
	v_add_f32_dpp v86, v86, v86 row_shl:4 row_mask:0xf bank_mask:0x5 bound_ctrl:1
	v_add_f32_dpp v86, v90, v90 row_shr:4 row_mask:0xf bank_mask:0xa bound_ctrl:1
	v_add_f32_dpp v87, v87, v87 row_shl:4 row_mask:0xf bank_mask:0x5 bound_ctrl:1
	v_add_f32_dpp v87, v91, v91 row_shr:4 row_mask:0xf bank_mask:0xa bound_ctrl:1
	v_add_f32_dpp v88, v88, v88 row_shl:4 row_mask:0xf bank_mask:0x5 bound_ctrl:1
	v_add_f32_dpp v88, v92, v92 row_shr:4 row_mask:0xf bank_mask:0xa bound_ctrl:1
	v_add_f32_dpp v89, v89, v89 row_shl:4 row_mask:0xf bank_mask:0x5 bound_ctrl:1
	v_add_f32_dpp v89, v93, v93 row_shr:4 row_mask:0xf bank_mask:0xa bound_ctrl:1
	v_add_f32_dpp v86, v86, v86 quad_perm:[2,3,0,1] row_mask:0xf bank_mask:0xf bound_ctrl:1
	v_add_f32_dpp v87, v87, v87 quad_perm:[2,3,0,1] row_mask:0xf bank_mask:0xf bound_ctrl:1
	v_add_f32_dpp v88, v88, v88 quad_perm:[2,3,0,1] row_mask:0xf bank_mask:0xf bound_ctrl:1
	v_add_f32_dpp v89, v89, v89 quad_perm:[2,3,0,1] row_mask:0xf bank_mask:0xf bound_ctrl:1
	v_cndmask_b32_e32 v86, v86, v88, vcc
	v_cndmask_b32_e32 v87, v87, v89, vcc
	v_cmp_ne_u32_e32 vcc, 0, v142
	v_add_f32_dpp v86, v86, v86 quad_perm:[1,0,3,2] row_mask:0xf bank_mask:0xf bound_ctrl:1
	v_add_f32_dpp v87, v87, v87 quad_perm:[1,0,3,2] row_mask:0xf bank_mask:0xf bound_ctrl:1
	v_cndmask_b32_e32 v86, v86, v87, vcc
	ds_write_b32 v52, v86
	s_branch .LBB0_167

; #define PG8_STAGE(bufoff, gbase, voff) do { _Pragma("unroll") for (int _i = 0; _i < 2; ++_i) \
;         __builtin_amdgcn_global_load_lds((const unsigned*)((const char*)(gbase) + (voff)[_i]), (PG8_LAS unsigned*)(lds + (bufoff) + ldsw + _i * 8192), 16, 0, 0); } while (0)
; #define PG8_LDA(dst, b, h) do { _Pragma("unroll") for (int m = 0; m < 4; ++m) _Pragma("unroll") for (int k = 0; k < 2; ++k) dst[m][k] = *(const PG8_LAS bf16x8*)(lds + PG8_SA(b, h) + aoff + m * 2048 + k * 1024); } while (0)
; #define PG8_LDB(dst, b, h) do { _Pragma("unroll") for (int n = 0; n < 2; ++n) _Pragma("unroll") for (int k = 0; k < 2; ++k) dst[n][k] = *(const PG8_LAS bf16x8*)(lds + PG8_SB(b, h) + boff + n * 2048 + k * 1024); } while (0)
; #define PG8_MMA(ai, bj, At, Bt) do { __builtin_amdgcn_s_setprio(1); _Pragma("unroll") for (int m = 0; m < 4; ++m) _Pragma("unroll") for (int n = 0; n < 2; ++n) _Pragma("unroll") for (int k = 0; k < 2; ++k) \
;         acc[ai][bj][m][n] = __builtin_amdgcn_mfma_f32_16x16x32_bf16(Bt[n][k], At[m][k], acc[ai][bj][m][n], 0, 0, 0); __builtin_amdgcn_s_setprio(0); } while (0)
; #define PG8_BAR __builtin_amdgcn_s_barrier()
; template <class Epi, class Sched, bool ALIGN_EPI = false, bool SP2 = false>
; __device__ __forceinline__ void gemm_phase(PG8_LAS unsigned char* lds, const Gemm g, const Sched& S, const Epi& E) {
;     ...
;         for (int t = 0; t < nt; t += 2) {
;             const bool last = (t == nt - 2);
;             const char* a1 = cA + (size_t)(t + 1) * kstep;
;             const char* a2 = last ? nA : cA + (size_t)(t + 2) * kstep; const char* b2 = last ? nB : cB + (size_t)(t + 2) * kstep;
;             const char* a3 = a2 + kstep; const char* b3 = b2 + kstep;
;             if (last && has_next) S.a_ready(nxt);
;             if constexpr (Epi::MID) { if (t == nt / 2) E.mid(acc, cur, wr, wc, fr, fq); }
;             if constexpr (SP2) {
;             PG8_LDB(B0, 0, 0); PG8_LDB(B1, 0, 1); PG8_SCHED; PG8_LDA(At, 0, 0); PG8_STAGE(PG8_SA(1, 1), a1 + hstep, voffA);
;             PG8_WAIT_V(8); PG8_WAIT_L(0); PG8_BAR; PG8_MMA(0, 0, At, B0); PG8_MMA(0, 1, At, B1); PG8_BAR; PG8_SCHED;
;             PG8_LDA(At, 0, 1); PG8_STAGE(PG8_SB(0, 0), b2, voffB); PG8_STAGE(PG8_SB(0, 1), b2 + hstep, voffB); PG8_STAGE(PG8_SA(0, 0), a2, voffA);
;             PG8_WAIT_V(8); PG8_WAIT_L(0); PG8_BAR; PG8_MMA(1, 0, At, B0); PG8_MMA(1, 1, At, B1); PG8_BAR; PG8_SCHED;
.LBB0_418:
	s_add_u32 s56, s40, 0xfff80080
	s_addc_u32 s57, s41, -1
	s_add_i32 s75, 0, 0x10000
	s_cmp_eq_u32 s74, 28
	s_cselect_b32 s59, s2, s57
	s_cselect_b32 s58, s3, s56
	v_add_u32_e32 v142, s75, v156
	s_cselect_b32 s57, s49, s73
	s_cselect_b32 s56, s51, s72
	s_add_i32 s78, 0, 0x14000
	ds_read_b128 v[152:155], v142
	ds_read_b128 v[160:163], v142 offset:1024
	ds_read_b128 v[164:167], v142 offset:2048
	ds_read_b128 v[182:185], v142 offset:3072
	v_add_u32_e32 v142, s78, v156
	ds_read_b128 v[186:189], v142
	ds_read_b128 v[190:193], v142 offset:1024
	ds_read_b128 v[194:197], v142 offset:2048
	ds_read_b128 v[198:201], v142 offset:3072
	v_lshl_add_u64 v[168:169], s[40:41], 0, v[150:151]
	s_add_i32 m0, s63, 0xc000
	ds_read_b128 v[202:205], v158
	ds_read_b128 v[206:209], v158 offset:1024
	ds_read_b128 v[214:217], v158 offset:2048
	ds_read_b128 v[218:221], v158 offset:3072
	ds_read_b128 v[222:225], v158 offset:4096
	ds_read_b128 v[226:229], v158 offset:5120
	ds_read_b128 v[230:233], v158 offset:6144
	ds_read_b128 v[234:237], v158 offset:7168
	global_load_lds_dwordx4 v[168:169], off
	v_lshl_add_u64 v[168:169], s[40:41], 0, v[136:137]
	s_add_i32 m0, s63, 0xe000
	s_nop 0
	global_load_lds_dwordx4 v[168:169], off
	s_waitcnt vmcnt(8)
	s_waitcnt lgkmcnt(0)
	s_setprio 1
	s_barrier
	v_mfma_f32_16x16x32_bf16 v[126:129], v[152:155], v[202:205], v[126:129]
	v_mfma_f32_16x16x32_bf16 v[122:125], v[164:167], v[202:205], v[122:125]
	v_mfma_f32_16x16x32_bf16 v[110:113], v[152:155], v[214:217], v[110:113]
	v_mfma_f32_16x16x32_bf16 v[106:109], v[164:167], v[214:217], v[106:109]
	v_mfma_f32_16x16x32_bf16 v[94:97], v[152:155], v[222:225], v[94:97]
	v_mfma_f32_16x16x32_bf16 v[90:93], v[164:167], v[222:225], v[90:93]
	v_mfma_f32_16x16x32_bf16 v[78:81], v[152:155], v[230:233], v[78:81]
	v_mfma_f32_16x16x32_bf16 v[74:77], v[164:167], v[230:233], v[74:77]
	v_mfma_f32_16x16x32_bf16 v[126:129], v[160:163], v[206:209], v[126:129]
	v_mfma_f32_16x16x32_bf16 v[122:125], v[182:185], v[206:209], v[122:125]
	v_mfma_f32_16x16x32_bf16 v[110:113], v[160:163], v[218:221], v[110:113]
	v_mfma_f32_16x16x32_bf16 v[106:109], v[182:185], v[218:221], v[106:109]
	v_mfma_f32_16x16x32_bf16 v[94:97], v[160:163], v[226:229], v[94:97]
	v_mfma_f32_16x16x32_bf16 v[90:93], v[182:185], v[226:229], v[90:93]
	v_mfma_f32_16x16x32_bf16 v[78:81], v[160:163], v[234:237], v[78:81]
	v_mfma_f32_16x16x32_bf16 v[74:77], v[182:185], v[234:237], v[74:77]
	s_setprio 0
	s_setprio 1
	v_mfma_f32_16x16x32_bf16 v[118:121], v[186:189], v[202:205], v[118:121]
	v_mfma_f32_16x16x32_bf16 v[114:117], v[194:197], v[202:205], v[114:117]
	v_mfma_f32_16x16x32_bf16 v[102:105], v[186:189], v[214:217], v[102:105]
	v_mfma_f32_16x16x32_bf16 v[98:101], v[194:197], v[214:217], v[98:101]
	v_mfma_f32_16x16x32_bf16 v[86:89], v[186:189], v[222:225], v[86:89]
	v_mfma_f32_16x16x32_bf16 v[82:85], v[194:197], v[222:225], v[82:85]
	v_mfma_f32_16x16x32_bf16 v[70:73], v[186:189], v[230:233], v[70:73]
	v_mfma_f32_16x16x32_bf16 v[66:69], v[194:197], v[230:233], v[66:69]
	v_mfma_f32_16x16x32_bf16 v[118:121], v[190:193], v[206:209], v[118:121]
	v_mfma_f32_16x16x32_bf16 v[114:117], v[198:201], v[206:209], v[114:117]
	v_mfma_f32_16x16x32_bf16 v[102:105], v[190:193], v[218:221], v[102:105]
	v_mfma_f32_16x16x32_bf16 v[98:101], v[198:201], v[218:221], v[98:101]
	v_mfma_f32_16x16x32_bf16 v[86:89], v[190:193], v[226:229], v[86:89]
	v_mfma_f32_16x16x32_bf16 v[82:85], v[198:201], v[226:229], v[82:85]
	v_mfma_f32_16x16x32_bf16 v[70:73], v[190:193], v[234:237], v[70:73]
	v_mfma_f32_16x16x32_bf16 v[66:69], v[198:201], v[234:237], v[66:69]
	s_setprio 0
	s_barrier
	s_add_i32 s75, s75, s62
	v_lshl_add_u64 v[168:169], s[56:57], 0, v[0:1]
	s_mov_b32 m0, s75
	ds_read_b128 v[202:205], v158 offset:16384
	ds_read_b128 v[206:209], v158 offset:17408
	ds_read_b128 v[214:217], v158 offset:18432
	ds_read_b128 v[218:221], v158 offset:19456
	ds_read_b128 v[222:225], v158 offset:20480
	ds_read_b128 v[226:229], v158 offset:21504
	ds_read_b128 v[230:233], v158 offset:22528
	ds_read_b128 v[234:237], v158 offset:23552
	global_load_lds_dwordx4 v[168:169], off
	s_add_i32 m0, s75, 0x2000
	s_add_u32 s76, s56, 0x80000
	v_lshl_add_u64 v[238:239], s[56:57], 0, v[130:131]
	s_addc_u32 s77, s57, 0
	s_add_i32 s75, s78, s62
	global_load_lds_dwordx4 v[238:239], off
	v_lshl_add_u64 v[240:241], s[76:77], 0, v[0:1]
	s_mov_b32 m0, s75
	v_lshl_add_u64 v[242:243], s[58:59], 0, v[132:133]
	global_load_lds_dwordx4 v[240:241], off
	v_lshl_add_u64 v[240:241], s[76:77], 0, v[130:131]
	s_add_i32 m0, s75, 0x2000
	s_nop 0
	global_load_lds_dwordx4 v[240:241], off
	v_lshl_add_u64 v[240:241], s[58:59], 0, v[134:135]
	s_mov_b32 m0, s63
	s_nop 0
	global_load_lds_dwordx4 v[240:241], off
	s_mov_b32 m0, s64
	s_nop 0
	global_load_lds_dwordx4 v[242:243], off
	s_waitcnt vmcnt(8)
	s_waitcnt lgkmcnt(0)
	s_setprio 1
	s_barrier
; #define PG8_STAGE(bufoff, gbase, voff) do { _Pragma("unroll") for (int _i = 0; _i < 2; ++_i) \
;         __builtin_amdgcn_global_load_lds((const unsigned*)((const char*)(gbase) + (voff)[_i]), (PG8_LAS unsigned*)(lds + (bufoff) + ldsw + _i * 8192), 16, 0, 0); } while (0)
; #define PG8_LDA(dst, b, h) do { _Pragma("unroll") for (int m = 0; m < 4; ++m) _Pragma("unroll") for (int k = 0; k < 2; ++k) dst[m][k] = *(const PG8_LAS bf16x8*)(lds + PG8_SA(b, h) + aoff + m * 2048 + k * 1024); } while (0)
; #define PG8_LDB(dst, b, h) do { _Pragma("unroll") for (int n = 0; n < 2; ++n) _Pragma("unroll") for (int k = 0; k < 2; ++k) dst[n][k] = *(const PG8_LAS bf16x8*)(lds + PG8_SB(b, h) + boff + n * 2048 + k * 1024); } while (0)
; #define PG8_MMA(ai, bj, At, Bt) do { __builtin_amdgcn_s_setprio(1); _Pragma("unroll") for (int m = 0; m < 4; ++m) _Pragma("unroll") for (int n = 0; n < 2; ++n) _Pragma("unroll") for (int k = 0; k < 2; ++k) \
;         acc[ai][bj][m][n] = __builtin_amdgcn_mfma_f32_16x16x32_bf16(Bt[n][k], At[m][k], acc[ai][bj][m][n], 0, 0, 0); __builtin_amdgcn_s_setprio(0); } while (0)
; #define PG8_WAIT_V(n) asm volatile("s_waitcnt vmcnt(" #n ")" ::: "memory")
; #define PG8_WAIT_L(n) asm volatile("s_waitcnt lgkmcnt(" #n ")" ::: "memory")
; #define PG8_BAR __builtin_amdgcn_s_barrier()
; #define PG8_SCHED __builtin_amdgcn_sched_barrier(0)
; template <class Epi, class Sched, bool ALIGN_EPI = false, bool SP2 = false>
; __device__ __forceinline__ void gemm_phase(PG8_LAS unsigned char* lds, const Gemm g, const Sched& S, const Epi& E) {
;     ...
;             PG8_WAIT_V(8); PG8_WAIT_L(0); PG8_BAR; PG8_MMA(1, 0, At, B0); PG8_MMA(1, 1, At, B1); PG8_BAR; PG8_SCHED;
;             PG8_LDB(B0, 1, 0); PG8_LDB(B1, 1, 1); PG8_SCHED; PG8_LDA(At, 1, 0); PG8_STAGE(PG8_SA(0, 1), a2 + hstep, voffA);
;             PG8_WAIT_V(8); PG8_WAIT_L(0); PG8_BAR; PG8_MMA(0, 0, At, B0); PG8_MMA(0, 1, At, B1); PG8_BAR; PG8_SCHED;
	v_mfma_f32_16x16x32_bf16 v[62:65], v[152:155], v[202:205], v[62:65]
	v_mfma_f32_16x16x32_bf16 v[58:61], v[164:167], v[202:205], v[58:61]
	v_mfma_f32_16x16x32_bf16 v[46:49], v[152:155], v[214:217], v[46:49]
	v_mfma_f32_16x16x32_bf16 v[42:45], v[164:167], v[214:217], v[42:45]
	v_mfma_f32_16x16x32_bf16 v[30:33], v[152:155], v[222:225], v[30:33]
	v_mfma_f32_16x16x32_bf16 v[26:29], v[164:167], v[222:225], v[26:29]
	v_mfma_f32_16x16x32_bf16 v[14:17], v[152:155], v[230:233], v[14:17]
	v_mfma_f32_16x16x32_bf16 v[10:13], v[164:167], v[230:233], v[10:13]
	v_mfma_f32_16x16x32_bf16 v[62:65], v[160:163], v[206:209], v[62:65]
	v_mfma_f32_16x16x32_bf16 v[58:61], v[182:185], v[206:209], v[58:61]
	v_mfma_f32_16x16x32_bf16 v[46:49], v[160:163], v[218:221], v[46:49]
	v_mfma_f32_16x16x32_bf16 v[42:45], v[182:185], v[218:221], v[42:45]
	v_mfma_f32_16x16x32_bf16 v[30:33], v[160:163], v[226:229], v[30:33]
	v_mfma_f32_16x16x32_bf16 v[26:29], v[182:185], v[226:229], v[26:29]
	v_mfma_f32_16x16x32_bf16 v[14:17], v[160:163], v[234:237], v[14:17]
	v_mfma_f32_16x16x32_bf16 v[10:13], v[182:185], v[234:237], v[10:13]
	s_setprio 0
	s_setprio 1
	v_mfma_f32_16x16x32_bf16 v[54:57], v[186:189], v[202:205], v[54:57]
	v_mfma_f32_16x16x32_bf16 v[50:53], v[194:197], v[202:205], v[50:53]
	v_mfma_f32_16x16x32_bf16 v[38:41], v[186:189], v[214:217], v[38:41]
	v_mfma_f32_16x16x32_bf16 v[34:37], v[194:197], v[214:217], v[34:37]
	v_mfma_f32_16x16x32_bf16 v[22:25], v[186:189], v[222:225], v[22:25]
	v_mfma_f32_16x16x32_bf16 v[18:21], v[194:197], v[222:225], v[18:21]
	v_mfma_f32_16x16x32_bf16 v[6:9], v[186:189], v[230:233], v[6:9]
	v_mfma_f32_16x16x32_bf16 v[2:5], v[194:197], v[230:233], v[2:5]
	v_mfma_f32_16x16x32_bf16 v[54:57], v[190:193], v[206:209], v[54:57]
	v_mfma_f32_16x16x32_bf16 v[50:53], v[198:201], v[206:209], v[50:53]
	v_mfma_f32_16x16x32_bf16 v[38:41], v[190:193], v[218:221], v[38:41]
	v_mfma_f32_16x16x32_bf16 v[34:37], v[198:201], v[218:221], v[34:37]
	v_mfma_f32_16x16x32_bf16 v[22:25], v[190:193], v[226:229], v[22:25]
	v_mfma_f32_16x16x32_bf16 v[18:21], v[198:201], v[226:229], v[18:21]
	v_mfma_f32_16x16x32_bf16 v[6:9], v[190:193], v[234:237], v[6:9]
	v_mfma_f32_16x16x32_bf16 v[2:5], v[198:201], v[234:237], v[2:5]
	s_setprio 0
	s_barrier
	s_add_i32 s75, 0, 0x18000
	v_add_u32_e32 v142, s75, v156
	s_add_i32 s76, 0, 0x1c000
	ds_read_b128 v[152:155], v142
	ds_read_b128 v[160:163], v142 offset:1024
	ds_read_b128 v[164:167], v142 offset:2048
	ds_read_b128 v[182:185], v142 offset:3072
	v_add_u32_e32 v142, s76, v156
	ds_read_b128 v[186:189], v142
	ds_read_b128 v[190:193], v142 offset:1024
	ds_read_b128 v[194:197], v142 offset:2048
	ds_read_b128 v[198:201], v142 offset:3072
	s_add_u32 s58, s58, 0x80000
	s_addc_u32 s59, s59, 0
	s_mov_b32 m0, s65
	v_lshl_add_u64 v[244:245], s[58:59], 0, v[134:135]
	ds_read_b128 v[202:205], v158 offset:32768
	ds_read_b128 v[206:209], v158 offset:33792
	ds_read_b128 v[214:217], v158 offset:34816
	ds_read_b128 v[218:221], v158 offset:35840
	ds_read_b128 v[222:225], v158 offset:36864
	ds_read_b128 v[226:229], v158 offset:37888
	ds_read_b128 v[230:233], v158 offset:38912
	ds_read_b128 v[234:237], v158 offset:39936
	global_load_lds_dwordx4 v[244:245], off
	v_lshl_add_u64 v[244:245], s[58:59], 0, v[132:133]
	s_mov_b32 m0, s66
	s_nop 0
	global_load_lds_dwordx4 v[244:245], off
	s_waitcnt vmcnt(8)
	s_waitcnt lgkmcnt(0)
	s_setprio 1
	s_barrier
	v_mfma_f32_16x16x32_bf16 v[126:129], v[152:155], v[202:205], v[126:129]
	v_mfma_f32_16x16x32_bf16 v[122:125], v[164:167], v[202:205], v[122:125]
	v_mfma_f32_16x16x32_bf16 v[110:113], v[152:155], v[214:217], v[110:113]
	v_mfma_f32_16x16x32_bf16 v[106:109], v[164:167], v[214:217], v[106:109]
	v_mfma_f32_16x16x32_bf16 v[94:97], v[152:155], v[222:225], v[94:97]
	v_mfma_f32_16x16x32_bf16 v[90:93], v[164:167], v[222:225], v[90:93]
	v_mfma_f32_16x16x32_bf16 v[78:81], v[152:155], v[230:233], v[78:81]
	v_mfma_f32_16x16x32_bf16 v[74:77], v[164:167], v[230:233], v[74:77]
	v_mfma_f32_16x16x32_bf16 v[126:129], v[160:163], v[206:209], v[126:129]
	v_mfma_f32_16x16x32_bf16 v[122:125], v[182:185], v[206:209], v[122:125]
	v_mfma_f32_16x16x32_bf16 v[110:113], v[160:163], v[218:221], v[110:113]
	v_mfma_f32_16x16x32_bf16 v[106:109], v[182:185], v[218:221], v[106:109]
	v_mfma_f32_16x16x32_bf16 v[94:97], v[160:163], v[226:229], v[94:97]
	v_mfma_f32_16x16x32_bf16 v[90:93], v[182:185], v[226:229], v[90:93]
	v_mfma_f32_16x16x32_bf16 v[78:81], v[160:163], v[234:237], v[78:81]
	v_mfma_f32_16x16x32_bf16 v[74:77], v[182:185], v[234:237], v[74:77]
	s_setprio 0
	s_setprio 1
	v_mfma_f32_16x16x32_bf16 v[118:121], v[186:189], v[202:205], v[118:121]
	v_mfma_f32_16x16x32_bf16 v[114:117], v[194:197], v[202:205], v[114:117]
	v_mfma_f32_16x16x32_bf16 v[102:105], v[186:189], v[214:217], v[102:105]
	v_mfma_f32_16x16x32_bf16 v[98:101], v[194:197], v[214:217], v[98:101]
	v_mfma_f32_16x16x32_bf16 v[86:89], v[186:189], v[222:225], v[86:89]
	v_mfma_f32_16x16x32_bf16 v[82:85], v[194:197], v[222:225], v[82:85]
	v_mfma_f32_16x16x32_bf16 v[70:73], v[186:189], v[230:233], v[70:73]
	v_mfma_f32_16x16x32_bf16 v[66:69], v[194:197], v[230:233], v[66:69]
	v_mfma_f32_16x16x32_bf16 v[118:121], v[190:193], v[206:209], v[118:121]
	v_mfma_f32_16x16x32_bf16 v[114:117], v[198:201], v[206:209], v[114:117]
	v_mfma_f32_16x16x32_bf16 v[102:105], v[190:193], v[218:221], v[102:105]
	v_mfma_f32_16x16x32_bf16 v[98:101], v[198:201], v[218:221], v[98:101]
	v_mfma_f32_16x16x32_bf16 v[86:89], v[190:193], v[226:229], v[86:89]
	v_mfma_f32_16x16x32_bf16 v[82:85], v[198:201], v[226:229], v[82:85]
	v_mfma_f32_16x16x32_bf16 v[70:73], v[190:193], v[234:237], v[70:73]
	v_mfma_f32_16x16x32_bf16 v[66:69], v[198:201], v[234:237], v[66:69]
	s_setprio 0
	s_barrier
; #define PG8_STAGE(bufoff, gbase, voff) do { _Pragma("unroll") for (int _i = 0; _i < 2; ++_i) \
;         __builtin_amdgcn_global_load_lds((const unsigned*)((const char*)(gbase) + (voff)[_i]), (PG8_LAS unsigned*)(lds + (bufoff) + ldsw + _i * 8192), 16, 0, 0); } while (0)
; #define PG8_LDA(dst, b, h) do { _Pragma("unroll") for (int m = 0; m < 4; ++m) _Pragma("unroll") for (int k = 0; k < 2; ++k) dst[m][k] = *(const PG8_LAS bf16x8*)(lds + PG8_SA(b, h) + aoff + m * 2048 + k * 1024); } while (0)
; #define PG8_MMA(ai, bj, At, Bt) do { __builtin_amdgcn_s_setprio(1); _Pragma("unroll") for (int m = 0; m < 4; ++m) _Pragma("unroll") for (int n = 0; n < 2; ++n) _Pragma("unroll") for (int k = 0; k < 2; ++k) \
;         acc[ai][bj][m][n] = __builtin_amdgcn_mfma_f32_16x16x32_bf16(Bt[n][k], At[m][k], acc[ai][bj][m][n], 0, 0, 0); __builtin_amdgcn_s_setprio(0); } while (0)
; #define PG8_WAIT_V(n) asm volatile("s_waitcnt vmcnt(" #n ")" ::: "memory")
; #define PG8_WAIT_L(n) asm volatile("s_waitcnt lgkmcnt(" #n ")" ::: "memory")
; #define PG8_BAR __builtin_amdgcn_s_barrier()
; #define PG8_SCHED __builtin_amdgcn_sched_barrier(0)
; template <class Epi, class Sched, bool ALIGN_EPI = false, bool SP2 = false>
; __device__ __forceinline__ void gemm_phase(PG8_LAS unsigned char* lds, const Gemm g, const Sched& S, const Epi& E) {
;     ...
;         for (int t = 0; t < nt; t += 2) {
;             const bool last = (t == nt - 2);
;             const char* a1 = cA + (size_t)(t + 1) * kstep;
;             const char* a2 = last ? nA : cA + (size_t)(t + 2) * kstep; const char* b2 = last ? nB : cB + (size_t)(t + 2) * kstep;
;     ...
;             PG8_LDA(At, 1, 1); PG8_STAGE(PG8_SB(1, 0), b3, voffB); PG8_STAGE(PG8_SB(1, 1), b3 + hstep, voffB); PG8_STAGE(PG8_SA(1, 0), a3, voffA);
;             PG8_WAIT_V(8); PG8_WAIT_L(0); PG8_BAR; PG8_MMA(1, 0, At, B0); PG8_MMA(1, 1, At, B1); PG8_BAR; PG8_SCHED;
	s_add_i32 s58, s75, s62
	v_lshl_add_u64 v[168:169], v[168:169], 0, s[34:35]
	s_mov_b32 m0, s58
	ds_read_b128 v[202:205], v158 offset:49152
	ds_read_b128 v[206:209], v158 offset:50176
	ds_read_b128 v[214:217], v158 offset:51200
	ds_read_b128 v[218:221], v158 offset:52224
	ds_read_b128 v[222:225], v158 offset:53248
	ds_read_b128 v[226:229], v158 offset:54272
	ds_read_b128 v[230:233], v158 offset:55296
	ds_read_b128 v[234:237], v158 offset:56320
	global_load_lds_dwordx4 v[168:169], off
	s_add_i32 m0, s58, 0x2000
	s_add_u32 s56, s56, 0x80080
	v_lshl_add_u64 v[168:169], v[238:239], 0, s[34:35]
	s_addc_u32 s57, s57, 0
	s_add_i32 s58, s76, s62
	global_load_lds_dwordx4 v[168:169], off
	v_lshl_add_u64 v[168:169], s[56:57], 0, v[0:1]
	s_mov_b32 m0, s58
	s_nop 0
	global_load_lds_dwordx4 v[168:169], off
	v_lshl_add_u64 v[168:169], s[56:57], 0, v[130:131]
	s_add_i32 m0, s58, 0x2000
	s_nop 0
	global_load_lds_dwordx4 v[168:169], off
	v_lshl_add_u64 v[168:169], v[240:241], 0, s[34:35]
	s_mov_b32 m0, s67
	s_nop 0
	global_load_lds_dwordx4 v[168:169], off
	v_lshl_add_u64 v[168:169], v[242:243], 0, s[34:35]
	s_mov_b32 m0, s68
	s_nop 0
	global_load_lds_dwordx4 v[168:169], off
	s_waitcnt vmcnt(8)
	s_waitcnt lgkmcnt(0)
	s_setprio 1
	s_barrier
	v_mfma_f32_16x16x32_bf16 v[62:65], v[152:155], v[202:205], v[62:65]
	v_mfma_f32_16x16x32_bf16 v[58:61], v[164:167], v[202:205], v[58:61]
	v_mfma_f32_16x16x32_bf16 v[46:49], v[152:155], v[214:217], v[46:49]
	v_mfma_f32_16x16x32_bf16 v[42:45], v[164:167], v[214:217], v[42:45]
	v_mfma_f32_16x16x32_bf16 v[30:33], v[152:155], v[222:225], v[30:33]
	v_mfma_f32_16x16x32_bf16 v[26:29], v[164:167], v[222:225], v[26:29]
	v_mfma_f32_16x16x32_bf16 v[14:17], v[152:155], v[230:233], v[14:17]
	v_mfma_f32_16x16x32_bf16 v[10:13], v[164:167], v[230:233], v[10:13]
	v_mfma_f32_16x16x32_bf16 v[62:65], v[160:163], v[206:209], v[62:65]
	v_mfma_f32_16x16x32_bf16 v[58:61], v[182:185], v[206:209], v[58:61]
	v_mfma_f32_16x16x32_bf16 v[46:49], v[160:163], v[218:221], v[46:49]
	v_mfma_f32_16x16x32_bf16 v[42:45], v[182:185], v[218:221], v[42:45]
	v_mfma_f32_16x16x32_bf16 v[30:33], v[160:163], v[226:229], v[30:33]
	v_mfma_f32_16x16x32_bf16 v[26:29], v[182:185], v[226:229], v[26:29]
	v_mfma_f32_16x16x32_bf16 v[14:17], v[160:163], v[234:237], v[14:17]
	v_mfma_f32_16x16x32_bf16 v[10:13], v[182:185], v[234:237], v[10:13]
	s_setprio 0
	s_setprio 1
	v_mfma_f32_16x16x32_bf16 v[54:57], v[186:189], v[202:205], v[54:57]
	v_mfma_f32_16x16x32_bf16 v[50:53], v[194:197], v[202:205], v[50:53]
	v_mfma_f32_16x16x32_bf16 v[38:41], v[186:189], v[214:217], v[38:41]
	v_mfma_f32_16x16x32_bf16 v[34:37], v[194:197], v[214:217], v[34:37]
	v_mfma_f32_16x16x32_bf16 v[22:25], v[186:189], v[222:225], v[22:25]
	v_mfma_f32_16x16x32_bf16 v[18:21], v[194:197], v[222:225], v[18:21]
	v_mfma_f32_16x16x32_bf16 v[6:9], v[186:189], v[230:233], v[6:9]
	v_mfma_f32_16x16x32_bf16 v[2:5], v[194:197], v[230:233], v[2:5]
	v_mfma_f32_16x16x32_bf16 v[54:57], v[190:193], v[206:209], v[54:57]
	v_mfma_f32_16x16x32_bf16 v[50:53], v[198:201], v[206:209], v[50:53]
	v_mfma_f32_16x16x32_bf16 v[38:41], v[190:193], v[218:221], v[38:41]
	v_mfma_f32_16x16x32_bf16 v[34:37], v[198:201], v[218:221], v[34:37]
	v_mfma_f32_16x16x32_bf16 v[22:25], v[190:193], v[226:229], v[22:25]
	v_mfma_f32_16x16x32_bf16 v[18:21], v[198:201], v[226:229], v[18:21]
	v_mfma_f32_16x16x32_bf16 v[6:9], v[190:193], v[234:237], v[6:9]
	v_mfma_f32_16x16x32_bf16 v[2:5], v[198:201], v[234:237], v[2:5]
	s_setprio 0
	s_barrier
	s_add_i32 s74, s74, 2
	s_add_u32 s72, s72, 0x100
	s_addc_u32 s73, s73, 0
	s_add_u32 s40, s40, 0x100
	s_addc_u32 s41, s41, 0
	s_cmp_gt_u32 s74, 29
	s_cbranch_scc0 .LBB0_418
	s_and_b64 vcc, exec, s[44:45]
	s_cbranch_vccz .LBB0_421
	s_barrier
